# NSA in-projection epilogue: the 8 per-row-block row-sum loads issued together
# speedup vs baseline: 1.0189x; 1.0189x over previous
; #define PG8_STAGE(bufoff, gbase, voff) do { _Pragma("unroll") for (int _i = 0; _i < 2; ++_i) \
;     __builtin_amdgcn_global_load_lds((const unsigned*)((const char*)(gbase) + (voff)[_i]), (LAS unsigned*)(lds + (bufoff) + ldsw + _i * 8192), 16, 0, 0); } while (0)
; #define PG8_LDB(dst, b, h) do { \
;     PG8_DSR(dst[0][0], baddr, ((b) * 2 + (h)) * PG_HTB + 0 * 2048 + 0);    PG8_DSR(dst[0][1], baddr, ((b) * 2 + (h)) * PG_HTB + 0 * 2048 + 1024); \
;     PG8_DSR(dst[1][0], baddr, ((b) * 2 + (h)) * PG_HTB + 1 * 2048 + 0);    PG8_DSR(dst[1][1], baddr, ((b) * 2 + (h)) * PG_HTB + 1 * 2048 + 1024); } while (0)
; #define PG8_WAIT_V(n) asm volatile("s_waitcnt vmcnt(" #n ")" ::: "memory")
; #define PG8_WAIT_L(n) asm volatile("s_waitcnt lgkmcnt(" #n ")" ::: "memory")
; template <class Epi>
; __device__ __forceinline__ void gemm_phase(LAS unsigned char* lds, const Gemm g, const StaticOrder& S, const Epi& E) {
;     ...
;     for (int t = 0; t < nt; t += 2) {
;       const bool last = (t == nt - 2);
;       const char* a1 = cA + (size_t)(t + 1) * kstep;
;       const char* a2 = last ? nA : cA + (size_t)(t + 2) * kstep; const char* b2 = last ? nB : cB + (size_t)(t + 2) * kstep;
;       const char* a3 = a2 + kstep; const char* b3 = b2 + kstep;
;       PG8_LDB(B0, 0, 0); PG8_SCHED; PG8_LDA(At, 0, 0); PG8_STAGE(PG8_SA(1, 1), a1 + hstep, voffA);
;       PG8_WAIT_L(8); PG8_BAR; PG8_WAIT_L0; PG8_MMA(0, 0, At, B0); PG8_BAR; PG8_SCHED;
;       PG8_LDB(B1, 0, 1); PG8_STAGE(PG8_SB(0, 0), b2, voffA);
;       PG8_BAR; PG8_WAIT_L0; PG8_MMA(0, 1, At, B1); PG8_BAR;
;       PG8_LDA(At, 0, 1); PG8_STAGE(PG8_SA(0, 0), a2, voffA);
;       PG8_BAR; PG8_WAIT_L0; PG8_MMA(1, 0, At, B0); PG8_BAR; PG8_SCHED;
;       PG8_STAGE(PG8_SB(0, 1), b2 + hstep, voffA);
;       PG8_WAIT_V(6); PG8_BAR; PG8_MMA(1, 1, At, B1); PG8_BAR;
;       PG8_LDB(B0, 1, 0); PG8_SCHED; PG8_LDA(At, 1, 0); PG8_STAGE(PG8_SA(0, 1), a2 + hstep, voffA);
;       PG8_WAIT_L(8); PG8_BAR; PG8_WAIT_L0; PG8_MMA(0, 0, At, B0); PG8_BAR; PG8_SCHED;
;       PG8_LDB(B1, 1, 1); PG8_STAGE(PG8_SB(1, 0), b3, voffA);
;       PG8_BAR; PG8_WAIT_L0; PG8_MMA(0, 1, At, B1); PG8_BAR;
;       PG8_LDA(At, 1, 1); PG8_STAGE(PG8_SA(1, 0), a3, voffA);
;       PG8_BAR; PG8_WAIT_L0; PG8_MMA(1, 0, At, B0); PG8_BAR; PG8_SCHED;
;       PG8_STAGE(PG8_SB(1, 1), b3 + hstep, voffA);
;       PG8_WAIT_V(6); PG8_BAR; PG8_MMA(1, 1, At, B1); PG8_BAR;
.LBB0_712:
	ds_read_b128 v[178:181], v157 offset:0
	ds_read_b128 v[182:185], v157 offset:0x400
	ds_read_b128 v[186:189], v157 offset:0x800
	s_add_u32 s10, s8, 0xfffc0080
	ds_read_b128 v[194:197], v157 offset:0xc00
	s_addc_u32 s11, s9, -1
	s_cmp_eq_u32 s35, 12
	s_cselect_b32 s39, s7, s11
	s_cselect_b32 s38, s18, s10
	ds_read_b128 v[198:201], v155 offset:0
	ds_read_b128 v[202:205], v155 offset:0x400
	ds_read_b128 v[206:209], v155 offset:0x800
	ds_read_b128 v[210:213], v155 offset:0xc00
	ds_read_b128 v[214:217], v155 offset:0x1000
	ds_read_b128 v[218:221], v155 offset:0x1400
	ds_read_b128 v[222:225], v155 offset:0x1800
	s_mov_b32 m0, s89
	ds_read_b128 v[226:229], v155 offset:0x1c00
	v_lshl_add_u64 v[2:3], s[8:9], 0, v[166:167]
	global_load_lds_dwordx4 v[2:3], off
	v_lshl_add_u64 v[2:3], s[8:9], 0, v[168:169]
	s_mov_b32 m0, s48
	s_cselect_b32 s11, s27, s34
	global_load_lds_dwordx4 v[2:3], off
	s_waitcnt lgkmcnt(8)
	s_barrier
	s_waitcnt lgkmcnt(0)
	s_cselect_b32 s10, s40, s41
	s_setprio 1
	v_mfma_f32_16x16x32_bf16 v[2:5], v[178:181], v[198:201], v[144:147]
	v_mfma_f32_16x16x32_bf16 v[6:9], v[186:189], v[198:201], v[140:143]
	v_mfma_f32_16x16x32_bf16 v[10:13], v[178:181], v[206:209], v[128:131]
	v_mfma_f32_16x16x32_bf16 v[14:17], v[186:189], v[206:209], v[124:127]
	v_mfma_f32_16x16x32_bf16 v[112:115], v[178:181], v[214:217], v[112:115]
	v_mfma_f32_16x16x32_bf16 v[108:111], v[186:189], v[214:217], v[108:111]
	v_mfma_f32_16x16x32_bf16 v[96:99], v[178:181], v[222:225], v[96:99]
	v_mfma_f32_16x16x32_bf16 v[92:95], v[186:189], v[222:225], v[92:95]
	v_mfma_f32_16x16x32_bf16 v[2:5], v[182:185], v[202:205], v[2:5]
	v_mfma_f32_16x16x32_bf16 v[6:9], v[194:197], v[202:205], v[6:9]
	v_mfma_f32_16x16x32_bf16 v[10:13], v[182:185], v[210:213], v[10:13]
	v_mfma_f32_16x16x32_bf16 v[14:17], v[194:197], v[210:213], v[14:17]
	v_mfma_f32_16x16x32_bf16 v[112:115], v[182:185], v[218:221], v[112:115]
	v_mfma_f32_16x16x32_bf16 v[108:111], v[194:197], v[218:221], v[108:111]
	v_mfma_f32_16x16x32_bf16 v[96:99], v[182:185], v[226:229], v[96:99]
	v_mfma_f32_16x16x32_bf16 v[92:95], v[194:197], v[226:229], v[92:95]
	s_setprio 0
	s_barrier
	ds_read_b128 v[124:127], v157 offset:0x4000
	ds_read_b128 v[128:131], v157 offset:0x4400
	ds_read_b128 v[140:143], v157 offset:0x4800
	s_mov_b32 m0, s25
	ds_read_b128 v[144:147], v157 offset:0x4c00
	v_lshl_add_u64 v[174:175], s[10:11], 0, v[148:149]
	global_load_lds_dwordx4 v[174:175], off
	v_lshl_add_u64 v[190:191], s[10:11], 0, v[150:151]
	s_mov_b32 m0, s90
	s_nop 0
	global_load_lds_dwordx4 v[190:191], off
	s_barrier
	s_waitcnt lgkmcnt(0)
	s_setprio 1
	v_mfma_f32_16x16x32_bf16 v[136:139], v[124:127], v[198:201], v[136:139]
	v_mfma_f32_16x16x32_bf16 v[132:135], v[140:143], v[198:201], v[132:135]
	v_mfma_f32_16x16x32_bf16 v[120:123], v[124:127], v[206:209], v[120:123]
	v_mfma_f32_16x16x32_bf16 v[116:119], v[140:143], v[206:209], v[116:119]
	v_mfma_f32_16x16x32_bf16 v[104:107], v[124:127], v[214:217], v[104:107]
	v_mfma_f32_16x16x32_bf16 v[100:103], v[140:143], v[214:217], v[100:103]
	v_mfma_f32_16x16x32_bf16 v[88:91], v[124:127], v[222:225], v[88:91]
	v_mfma_f32_16x16x32_bf16 v[84:87], v[140:143], v[222:225], v[84:87]
	v_mfma_f32_16x16x32_bf16 v[136:139], v[128:131], v[202:205], v[136:139]
	v_mfma_f32_16x16x32_bf16 v[132:135], v[144:147], v[202:205], v[132:135]
	v_mfma_f32_16x16x32_bf16 v[120:123], v[128:131], v[210:213], v[120:123]
	v_mfma_f32_16x16x32_bf16 v[116:119], v[144:147], v[210:213], v[116:119]
	v_mfma_f32_16x16x32_bf16 v[104:107], v[128:131], v[218:221], v[104:107]
	v_mfma_f32_16x16x32_bf16 v[100:103], v[144:147], v[218:221], v[100:103]
	v_mfma_f32_16x16x32_bf16 v[88:91], v[128:131], v[226:229], v[88:91]
	v_mfma_f32_16x16x32_bf16 v[84:87], v[144:147], v[226:229], v[84:87]
	s_setprio 0
	s_barrier
	ds_read_b128 v[198:201], v155 offset:0x4000
	ds_read_b128 v[202:205], v155 offset:0x4400
	ds_read_b128 v[206:209], v155 offset:0x4800
	ds_read_b128 v[210:213], v155 offset:0x4c00
	ds_read_b128 v[214:217], v155 offset:0x5000
	ds_read_b128 v[218:221], v155 offset:0x5400
	ds_read_b128 v[222:225], v155 offset:0x5800
	s_mov_b32 m0, s28
	ds_read_b128 v[226:229], v155 offset:0x5c00
	v_lshl_add_u64 v[230:231], s[38:39], 0, v[148:149]
	global_load_lds_dwordx4 v[230:231], off
	v_lshl_add_u64 v[232:233], s[38:39], 0, v[150:151]
	s_mov_b32 m0, s91
	s_nop 0
	global_load_lds_dwordx4 v[232:233], off
	s_barrier
	s_waitcnt lgkmcnt(0)
	s_setprio 1
	v_mfma_f32_16x16x32_bf16 v[80:83], v[178:181], v[198:201], v[80:83]
	v_mfma_f32_16x16x32_bf16 v[76:79], v[186:189], v[198:201], v[76:79]
	v_mfma_f32_16x16x32_bf16 v[64:67], v[178:181], v[206:209], v[64:67]
	v_mfma_f32_16x16x32_bf16 v[60:63], v[186:189], v[206:209], v[60:63]
	v_mfma_f32_16x16x32_bf16 v[48:51], v[178:181], v[214:217], v[48:51]
	v_mfma_f32_16x16x32_bf16 v[44:47], v[186:189], v[214:217], v[44:47]
	v_mfma_f32_16x16x32_bf16 v[32:35], v[178:181], v[222:225], v[32:35]
	v_mfma_f32_16x16x32_bf16 v[28:31], v[186:189], v[222:225], v[28:31]
	v_mfma_f32_16x16x32_bf16 v[80:83], v[182:185], v[202:205], v[80:83]
	v_mfma_f32_16x16x32_bf16 v[76:79], v[194:197], v[202:205], v[76:79]
	v_mfma_f32_16x16x32_bf16 v[64:67], v[182:185], v[210:213], v[64:67]
	v_mfma_f32_16x16x32_bf16 v[60:63], v[194:197], v[210:213], v[60:63]
	v_mfma_f32_16x16x32_bf16 v[48:51], v[182:185], v[218:221], v[48:51]
	v_mfma_f32_16x16x32_bf16 v[44:47], v[194:197], v[218:221], v[44:47]
	v_mfma_f32_16x16x32_bf16 v[32:35], v[182:185], v[226:229], v[32:35]
	v_mfma_f32_16x16x32_bf16 v[28:31], v[194:197], v[226:229], v[28:31]
	s_setprio 0
	s_barrier
; #define PG8_STAGE(bufoff, gbase, voff) do { _Pragma("unroll") for (int _i = 0; _i < 2; ++_i) \
;     __builtin_amdgcn_global_load_lds((const unsigned*)((const char*)(gbase) + (voff)[_i]), (LAS unsigned*)(lds + (bufoff) + ldsw + _i * 8192), 16, 0, 0); } while (0)
; #define PG8_LDB(dst, b, h) do { \
;     PG8_DSR(dst[0][0], baddr, ((b) * 2 + (h)) * PG_HTB + 0 * 2048 + 0);    PG8_DSR(dst[0][1], baddr, ((b) * 2 + (h)) * PG_HTB + 0 * 2048 + 1024); \
;     PG8_DSR(dst[1][0], baddr, ((b) * 2 + (h)) * PG_HTB + 1 * 2048 + 0);    PG8_DSR(dst[1][1], baddr, ((b) * 2 + (h)) * PG_HTB + 1 * 2048 + 1024); } while (0)
; #define PG8_MMA(ai, bj, At, Bt) do { __builtin_amdgcn_s_setprio(1); _Pragma("unroll") for (int m = 0; m < 4; ++m) _Pragma("unroll") for (int n = 0; n < 2; ++n) _Pragma("unroll") for (int k = 0; k < 2; ++k) \
;     acc[ai][bj][m][n] = __builtin_amdgcn_mfma_f32_16x16x32_bf16(Bt[n][k], At[m][k], acc[ai][bj][m][n], 0, 0, 0); __builtin_amdgcn_s_setprio(0); } while (0)
; #define PG8_WAIT_V(n) asm volatile("s_waitcnt vmcnt(" #n ")" ::: "memory")
; #define PG8_BAR __builtin_amdgcn_s_barrier()
; template <class Epi>
; __device__ __forceinline__ void gemm_phase(LAS unsigned char* lds, const Gemm g, const StaticOrder& S, const Epi& E) {
;     ...
;       PG8_LDB(B0, 0, 0); PG8_SCHED; PG8_LDA(At, 0, 0); PG8_STAGE(PG8_SA(1, 1), a1 + hstep, voffA);
;       PG8_WAIT_L(8); PG8_BAR; PG8_WAIT_L0; PG8_MMA(0, 0, At, B0); PG8_BAR; PG8_SCHED;
;       PG8_LDB(B1, 0, 1); PG8_STAGE(PG8_SB(0, 0), b2, voffA);
;       PG8_BAR; PG8_WAIT_L0; PG8_MMA(0, 1, At, B1); PG8_BAR;
;       PG8_LDA(At, 0, 1); PG8_STAGE(PG8_SA(0, 0), a2, voffA);
;       PG8_BAR; PG8_WAIT_L0; PG8_MMA(1, 0, At, B0); PG8_BAR; PG8_SCHED;
;       PG8_STAGE(PG8_SB(0, 1), b2 + hstep, voffA);
;       PG8_WAIT_V(6); PG8_BAR; PG8_MMA(1, 1, At, B1); PG8_BAR;
;       PG8_LDB(B0, 1, 0); PG8_SCHED; PG8_LDA(At, 1, 0); PG8_STAGE(PG8_SA(0, 1), a2 + hstep, voffA);
;       PG8_WAIT_L(8); PG8_BAR; PG8_WAIT_L0; PG8_MMA(0, 0, At, B0); PG8_BAR; PG8_SCHED;
;       PG8_LDB(B1, 1, 1); PG8_STAGE(PG8_SB(1, 0), b3, voffA);
;       PG8_BAR; PG8_WAIT_L0; PG8_MMA(0, 1, At, B1); PG8_BAR;
;       PG8_LDA(At, 1, 1); PG8_STAGE(PG8_SA(1, 0), a3, voffA);
;       PG8_BAR; PG8_WAIT_L0; PG8_MMA(1, 0, At, B0); PG8_BAR; PG8_SCHED;
;       PG8_STAGE(PG8_SB(1, 1), b3 + hstep, voffA);
;       PG8_WAIT_V(6); PG8_BAR; PG8_MMA(1, 1, At, B1); PG8_BAR;
	s_add_u32 s36, s10, 0x40000
	s_addc_u32 s37, s11, 0
	s_mov_b32 m0, s92
	v_lshl_add_u64 v[18:19], s[36:37], 0, v[148:149]
	global_load_lds_dwordx4 v[18:19], off
	v_lshl_add_u64 v[18:19], s[36:37], 0, v[150:151]
	s_mov_b32 m0, s93
	s_nop 0
	global_load_lds_dwordx4 v[18:19], off
	s_waitcnt vmcnt(6)
	s_barrier
	s_setprio 1
	v_mfma_f32_16x16x32_bf16 v[72:75], v[124:127], v[198:201], v[72:75]
	v_mfma_f32_16x16x32_bf16 v[68:71], v[140:143], v[198:201], v[68:71]
	v_mfma_f32_16x16x32_bf16 v[56:59], v[124:127], v[206:209], v[56:59]
	v_mfma_f32_16x16x32_bf16 v[52:55], v[140:143], v[206:209], v[52:55]
	v_mfma_f32_16x16x32_bf16 v[40:43], v[124:127], v[214:217], v[40:43]
	v_mfma_f32_16x16x32_bf16 v[36:39], v[140:143], v[214:217], v[36:39]
	v_mfma_f32_16x16x32_bf16 v[24:27], v[124:127], v[222:225], v[24:27]
	v_mfma_f32_16x16x32_bf16 v[18:21], v[140:143], v[222:225], v[20:23]
	v_mfma_f32_16x16x32_bf16 v[72:75], v[128:131], v[202:205], v[72:75]
	v_mfma_f32_16x16x32_bf16 v[68:71], v[144:147], v[202:205], v[68:71]
	v_mfma_f32_16x16x32_bf16 v[56:59], v[128:131], v[210:213], v[56:59]
	v_mfma_f32_16x16x32_bf16 v[52:55], v[144:147], v[210:213], v[52:55]
	v_mfma_f32_16x16x32_bf16 v[40:43], v[128:131], v[218:221], v[40:43]
	v_mfma_f32_16x16x32_bf16 v[36:39], v[144:147], v[218:221], v[36:39]
	v_mfma_f32_16x16x32_bf16 v[24:27], v[128:131], v[226:229], v[24:27]
	v_mfma_f32_16x16x32_bf16 v[20:23], v[144:147], v[226:229], v[18:21]
	s_setprio 0
	s_barrier
	ds_read_b128 v[178:181], v157 offset:0x8000
	ds_read_b128 v[182:185], v157 offset:0x8400
	ds_read_b128 v[186:189], v157 offset:0x8800
	ds_read_b128 v[194:197], v157 offset:0x8c00
	ds_read_b128 v[198:201], v155 offset:0x8000
	ds_read_b128 v[202:205], v155 offset:0x8400
	ds_read_b128 v[206:209], v155 offset:0x8800
	ds_read_b128 v[210:213], v155 offset:0x8c00
	ds_read_b128 v[214:217], v155 offset:0x9000
	ds_read_b128 v[218:221], v155 offset:0x9400
	s_add_u32 s36, s38, 0x40000
	ds_read_b128 v[222:225], v155 offset:0x9800
	s_addc_u32 s37, s39, 0
	s_mov_b32 m0, s94
	ds_read_b128 v[226:229], v155 offset:0x9c00
	v_lshl_add_u64 v[18:19], s[36:37], 0, v[148:149]
	global_load_lds_dwordx4 v[18:19], off
	v_lshl_add_u64 v[18:19], s[36:37], 0, v[150:151]
	s_mov_b32 m0, s95
	s_nop 0
	global_load_lds_dwordx4 v[18:19], off
	s_waitcnt lgkmcnt(8)
	s_barrier
	s_waitcnt lgkmcnt(0)
	s_setprio 1
	v_mfma_f32_16x16x32_bf16 v[2:5], v[178:181], v[198:201], v[2:5]
	v_mfma_f32_16x16x32_bf16 v[144:147], v[182:185], v[202:205], v[2:5]
	v_mfma_f32_16x16x32_bf16 v[2:5], v[186:189], v[198:201], v[6:9]
	v_mfma_f32_16x16x32_bf16 v[140:143], v[194:197], v[202:205], v[2:5]
	v_mfma_f32_16x16x32_bf16 v[2:5], v[178:181], v[206:209], v[10:13]
	v_mfma_f32_16x16x32_bf16 v[128:131], v[182:185], v[210:213], v[2:5]
	v_mfma_f32_16x16x32_bf16 v[2:5], v[186:189], v[206:209], v[14:17]
	v_mfma_f32_16x16x32_bf16 v[124:127], v[194:197], v[210:213], v[2:5]
	v_mfma_f32_16x16x32_bf16 v[2:5], v[178:181], v[214:217], v[112:115]
	v_mfma_f32_16x16x32_bf16 v[112:115], v[182:185], v[218:221], v[2:5]
	v_mfma_f32_16x16x32_bf16 v[2:5], v[186:189], v[214:217], v[108:111]
	v_mfma_f32_16x16x32_bf16 v[108:111], v[194:197], v[218:221], v[2:5]
	v_mfma_f32_16x16x32_bf16 v[2:5], v[178:181], v[222:225], v[96:99]
	v_mfma_f32_16x16x32_bf16 v[96:99], v[182:185], v[226:229], v[2:5]
	v_mfma_f32_16x16x32_bf16 v[2:5], v[186:189], v[222:225], v[92:95]
	v_mfma_f32_16x16x32_bf16 v[92:95], v[194:197], v[226:229], v[2:5]
	s_setprio 0
	s_barrier
	ds_read_b128 v[16:19], v157 offset:0xc000
	ds_read_b128 v[12:15], v157 offset:0xc400
	ds_read_b128 v[8:11], v157 offset:0xc800
	s_mov_b32 m0, s46
	ds_read_b128 v[4:7], v157 offset:0xcc00
	s_nop 3
	v_lshl_add_u64 v[2:3], v[174:175], 0, s[16:17]
	global_load_lds_dwordx4 v[2:3], off
	v_lshl_add_u64 v[2:3], v[190:191], 0, s[16:17]
	s_mov_b32 m0, s0
	s_nop 0
	global_load_lds_dwordx4 v[2:3], off
	s_barrier
	s_waitcnt lgkmcnt(0)
	s_setprio 1
	v_mfma_f32_16x16x32_bf16 v[136:139], v[16:19], v[198:201], v[136:139]
	v_mfma_f32_16x16x32_bf16 v[132:135], v[8:11], v[198:201], v[132:135]
	v_mfma_f32_16x16x32_bf16 v[120:123], v[16:19], v[206:209], v[120:123]
	v_mfma_f32_16x16x32_bf16 v[116:119], v[8:11], v[206:209], v[116:119]
	v_mfma_f32_16x16x32_bf16 v[104:107], v[16:19], v[214:217], v[104:107]
	v_mfma_f32_16x16x32_bf16 v[100:103], v[8:11], v[214:217], v[100:103]
	v_mfma_f32_16x16x32_bf16 v[88:91], v[16:19], v[222:225], v[88:91]
	v_mfma_f32_16x16x32_bf16 v[84:87], v[8:11], v[222:225], v[84:87]
	v_mfma_f32_16x16x32_bf16 v[136:139], v[12:15], v[202:205], v[136:139]
	v_mfma_f32_16x16x32_bf16 v[132:135], v[4:7], v[202:205], v[132:135]
	v_mfma_f32_16x16x32_bf16 v[120:123], v[12:15], v[210:213], v[120:123]
	v_mfma_f32_16x16x32_bf16 v[116:119], v[4:7], v[210:213], v[116:119]
	v_mfma_f32_16x16x32_bf16 v[104:107], v[12:15], v[218:221], v[104:107]
	v_mfma_f32_16x16x32_bf16 v[100:103], v[4:7], v[218:221], v[100:103]
	v_mfma_f32_16x16x32_bf16 v[88:91], v[12:15], v[226:229], v[88:91]
	v_mfma_f32_16x16x32_bf16 v[84:87], v[4:7], v[226:229], v[84:87]
	s_setprio 0
	s_barrier
	ds_read_b128 v[198:201], v155 offset:0xc000
	ds_read_b128 v[202:205], v155 offset:0xc400
	ds_read_b128 v[206:209], v155 offset:0xc800
	ds_read_b128 v[210:213], v155 offset:0xcc00
	ds_read_b128 v[214:217], v155 offset:0xd000
	ds_read_b128 v[218:221], v155 offset:0xd400
	ds_read_b128 v[222:225], v155 offset:0xd800
	s_mov_b32 m0, s1
	ds_read_b128 v[226:229], v155 offset:0xdc00
	v_lshl_add_u64 v[2:3], v[230:231], 0, s[16:17]
	global_load_lds_dwordx4 v[2:3], off
	v_lshl_add_u64 v[2:3], v[232:233], 0, s[16:17]
	s_mov_b32 m0, s62
	s_nop 0
	global_load_lds_dwordx4 v[2:3], off
	s_barrier
; #define PG8_STAGE(bufoff, gbase, voff) do { _Pragma("unroll") for (int _i = 0; _i < 2; ++_i) \
;     __builtin_amdgcn_global_load_lds((const unsigned*)((const char*)(gbase) + (voff)[_i]), (LAS unsigned*)(lds + (bufoff) + ldsw + _i * 8192), 16, 0, 0); } while (0)
; #define PG8_MMA(ai, bj, At, Bt) do { __builtin_amdgcn_s_setprio(1); _Pragma("unroll") for (int m = 0; m < 4; ++m) _Pragma("unroll") for (int n = 0; n < 2; ++n) _Pragma("unroll") for (int k = 0; k < 2; ++k) \
;     acc[ai][bj][m][n] = __builtin_amdgcn_mfma_f32_16x16x32_bf16(Bt[n][k], At[m][k], acc[ai][bj][m][n], 0, 0, 0); __builtin_amdgcn_s_setprio(0); } while (0)
; #define PG8_WAIT_V(n) asm volatile("s_waitcnt vmcnt(" #n ")" ::: "memory")
; #define PG8_WAIT_L0 asm volatile("s_waitcnt lgkmcnt(0)" \
;     : "+v"(At[0][0]), "+v"(At[0][1]), "+v"(At[1][0]), "+v"(At[1][1]), "+v"(At[2][0]), "+v"(At[2][1]), "+v"(At[3][0]), "+v"(At[3][1]), \
;       "+v"(B0[0][0]), "+v"(B0[0][1]), "+v"(B0[1][0]), "+v"(B0[1][1]), "+v"(B1[0][0]), "+v"(B1[0][1]), "+v"(B1[1][0]), "+v"(B1[1][1]) :: "memory")
; #define PG8_BAR __builtin_amdgcn_s_barrier()
; #define PG8_SCHED __builtin_amdgcn_sched_barrier(0)
; template <class Epi>
; __device__ __forceinline__ void gemm_phase(LAS unsigned char* lds, const Gemm g, const StaticOrder& S, const Epi& E) {
;     ...
;       PG8_BAR; PG8_WAIT_L0; PG8_MMA(1, 0, At, B0); PG8_BAR; PG8_SCHED;
;       PG8_STAGE(PG8_SB(1, 1), b3 + hstep, voffA);
;       PG8_WAIT_V(6); PG8_BAR; PG8_MMA(1, 1, At, B1); PG8_BAR;
	s_waitcnt lgkmcnt(0)
	s_setprio 1
	v_mfma_f32_16x16x32_bf16 v[80:83], v[178:181], v[198:201], v[80:83]
	v_mfma_f32_16x16x32_bf16 v[76:79], v[186:189], v[198:201], v[76:79]
	v_mfma_f32_16x16x32_bf16 v[64:67], v[178:181], v[206:209], v[64:67]
	v_mfma_f32_16x16x32_bf16 v[60:63], v[186:189], v[206:209], v[60:63]
	v_mfma_f32_16x16x32_bf16 v[48:51], v[178:181], v[214:217], v[48:51]
	v_mfma_f32_16x16x32_bf16 v[44:47], v[186:189], v[214:217], v[44:47]
	v_mfma_f32_16x16x32_bf16 v[32:35], v[178:181], v[222:225], v[32:35]
	v_mfma_f32_16x16x32_bf16 v[28:31], v[186:189], v[222:225], v[28:31]
	v_mfma_f32_16x16x32_bf16 v[80:83], v[182:185], v[202:205], v[80:83]
	v_mfma_f32_16x16x32_bf16 v[76:79], v[194:197], v[202:205], v[76:79]
	v_mfma_f32_16x16x32_bf16 v[64:67], v[182:185], v[210:213], v[64:67]
	v_mfma_f32_16x16x32_bf16 v[60:63], v[194:197], v[210:213], v[60:63]
	v_mfma_f32_16x16x32_bf16 v[48:51], v[182:185], v[218:221], v[48:51]
	v_mfma_f32_16x16x32_bf16 v[44:47], v[194:197], v[218:221], v[44:47]
	v_mfma_f32_16x16x32_bf16 v[32:35], v[182:185], v[226:229], v[32:35]
	v_mfma_f32_16x16x32_bf16 v[28:31], v[194:197], v[226:229], v[28:31]
	s_setprio 0
	s_barrier
	s_add_u32 s10, s10, 0x40080
	s_addc_u32 s11, s11, 0
	s_mov_b32 m0, s63
	v_lshl_add_u64 v[2:3], s[10:11], 0, v[148:149]
	global_load_lds_dwordx4 v[2:3], off
	v_lshl_add_u64 v[2:3], s[10:11], 0, v[150:151]
	s_mov_b32 m0, s78
	s_nop 0
	global_load_lds_dwordx4 v[2:3], off
	s_waitcnt vmcnt(6)
	s_barrier
	s_setprio 1
	v_mfma_f32_16x16x32_bf16 v[72:75], v[16:19], v[198:201], v[72:75]
	v_mfma_f32_16x16x32_bf16 v[68:71], v[8:11], v[198:201], v[68:71]
	v_mfma_f32_16x16x32_bf16 v[56:59], v[16:19], v[206:209], v[56:59]
	v_mfma_f32_16x16x32_bf16 v[52:55], v[8:11], v[206:209], v[52:55]
	v_mfma_f32_16x16x32_bf16 v[40:43], v[16:19], v[214:217], v[40:43]
	v_mfma_f32_16x16x32_bf16 v[36:39], v[8:11], v[214:217], v[36:39]
	v_mfma_f32_16x16x32_bf16 v[24:27], v[16:19], v[222:225], v[24:27]
	v_mfma_f32_16x16x32_bf16 v[20:23], v[8:11], v[222:225], v[20:23]
	v_mfma_f32_16x16x32_bf16 v[72:75], v[12:15], v[202:205], v[72:75]
	v_mfma_f32_16x16x32_bf16 v[68:71], v[4:7], v[202:205], v[68:71]
	v_mfma_f32_16x16x32_bf16 v[56:59], v[12:15], v[210:213], v[56:59]
	v_mfma_f32_16x16x32_bf16 v[52:55], v[4:7], v[210:213], v[52:55]
	v_mfma_f32_16x16x32_bf16 v[40:43], v[12:15], v[218:221], v[40:43]
	v_mfma_f32_16x16x32_bf16 v[36:39], v[4:7], v[218:221], v[36:39]
	v_mfma_f32_16x16x32_bf16 v[24:27], v[12:15], v[226:229], v[24:27]
	v_mfma_f32_16x16x32_bf16 v[20:23], v[4:7], v[226:229], v[20:23]
	s_setprio 0
	s_add_i32 s35, s35, 2
	s_add_u32 s8, s8, 0x100
	s_addc_u32 s9, s9, 0
	s_add_u32 s41, s41, 0x100
	s_addc_u32 s34, s34, 0
	s_cmp_gt_u32 s35, 13
	s_barrier
	s_cbranch_scc0 .LBB0_712
; __device__ __forceinline__ uint2 pack4(f32x4 v) { return make_uint2(pack2(v[0], v[1]), pack2(v[2], v[3])); }
; __device__ __forceinline__ float rstd_of(const unsigned long long* rowss, int row) {
;   return rsqrtf((float)rowss[row] * (1.f / (SS_FIX * DM)) + 1e-6f);
; }
;   __device__ __forceinline__ void operator()(const AccT& acc_in, const Unit& u, int wr, int wc, int fr, int fq) const {
;     ...
;     for (int ai = 0; ai < 2; ++ai)
; #pragma unroll
;       for (int m = 0; m < 4; ++m) {
;         const int tok = EPI_ROW(u, ai, m);
;         const float rs = rstd_of(rowss, tok);
;         f32x4 acc[2][2][2];
; #pragma unroll
;         for (int bj = 0; bj < 2; ++bj)
; #pragma unroll
;           for (int n = 0; n < 2; ++n) acc[0][bj][n] = acc_in[ai][bj][m][n] * rs;
;         if (u.pn < 4) {
; #pragma unroll
;           for (int bj = 0; bj < 2; ++bj) {
;             const int head = 4 * u.pn + 2 * bj + (wc >> 1);
;             rope_store(acc[0][bj][0], acc[0][bj][1], tok, d1, qn + (size_t)tok * DM + head * 64);
;           }
;         } else if (u.pn == 4) {
; #pragma unroll
;           for (int bj = 0; bj < 2; ++bj)
; #pragma unroll
;             for (int n = 0; n < 2; ++n) *(uint2*)(cbuf + (size_t)tok * 256 + (EPI_COL(u, bj, n) - 1024)) = pack4(acc[0][bj][n]);
;         } else if (u.pn < 7) {
;           u16* kdst = (u.pn == 5) ? ksb : kwb;
;           u16* vdst = (u.pn == 5) ? vsT : vwT;
;           const int gk = wc >> 1;
;           rope_store(acc[0][0][0], acc[0][0][1], tok, d1, kdst + (size_t)tok * 128 + gk * 64);
;           const int b = tok >> 12, t = tok & 4095;
; #pragma unroll
;           for (int n = 0; n < 2; ++n) {
;             const int d = 32 * (wc & 1) + 16 * n + 4 * fq;
; #pragma unroll
;             for (int r = 0; r < 4; ++r) vdst[((size_t)(b * 2 + gk) * 64 + d + r) * SEQ + t] = f2bf(acc[0][1][n][r]);
;           }
;         } else {
; #pragma unroll
;           for (int n = 0; n < 2; ++n) {
;             const int c = 32 * wc + 16 * n + 4 * fq;
;             if (c < 48) {
;               const f32x4 a = acc[0][0][n];
;               float4 gv;
;               gv.x = 1.f / (1.f + __expf(-a[0])); gv.y = 1.f / (1.f + __expf(-a[1]));
;               gv.z = 1.f / (1.f + __expf(-a[2])); gv.w = 1.f / (1.f + __expf(-a[3]));
;               *(float4*)(gbuf + (size_t)tok * 48 + c) = gv;
;             }
;           }
;         }
	s_lshl_b32 s27, s6, 8
	s_add_i32 s27, s27, s49
	v_or_b32_e32 v2, s27, v153
	v_ashrrev_i32_e32 v3, 31, v2
	v_lshl_add_u64 v[174:175], v[2:3], 3, s[12:13]
	global_load_dwordx2 v[174:175], v[174:175], off
	v_add_u32_e32 v248, 16, v2
	v_ashrrev_i32_e32 v249, 31, v248
	v_lshl_add_u64 v[248:249], v[248:249], 3, s[12:13]
	global_load_dwordx2 v[234:235], v[248:249], off
	v_add_u32_e32 v248, 32, v2
	v_ashrrev_i32_e32 v249, 31, v248
	v_lshl_add_u64 v[248:249], v[248:249], 3, s[12:13]
	global_load_dwordx2 v[236:237], v[248:249], off
	v_add_u32_e32 v248, 48, v2
	v_ashrrev_i32_e32 v249, 31, v248
	v_lshl_add_u64 v[248:249], v[248:249], 3, s[12:13]
	global_load_dwordx2 v[238:239], v[248:249], off
	v_add_u32_e32 v248, 128, v2
	v_ashrrev_i32_e32 v249, 31, v248
	v_lshl_add_u64 v[248:249], v[248:249], 3, s[12:13]
	global_load_dwordx2 v[240:241], v[248:249], off
	v_add_u32_e32 v248, 144, v2
	v_ashrrev_i32_e32 v249, 31, v248
	v_lshl_add_u64 v[248:249], v[248:249], 3, s[12:13]
	global_load_dwordx2 v[242:243], v[248:249], off
	v_add_u32_e32 v248, 160, v2
	v_ashrrev_i32_e32 v249, 31, v248
	v_lshl_add_u64 v[248:249], v[248:249], 3, s[12:13]
	global_load_dwordx2 v[244:245], v[248:249], off
	v_add_u32_e32 v248, 176, v2
	v_ashrrev_i32_e32 v249, 31, v248
	v_lshl_add_u64 v[248:249], v[248:249], 3, s[12:13]
	global_load_dwordx2 v[246:247], v[248:249], off
	s_cmp_gt_i32 s24, 3
	s_cselect_b64 s[10:11], -1, 0
	s_cmp_lg_u32 s24, 4
	s_cselect_b64 s[8:9], -1, 0
	s_cmp_gt_u32 s24, 6
	s_cselect_b64 s[66:67], -1, 0
	s_cmp_eq_u32 s24, 5
	s_cselect_b64 s[60:61], -1, 0
	s_ashr_i32 s6, s27, 11
	s_and_b32 s6, s6, -2
	s_or_b32 s6, s6, s79
	s_ashr_i32 s7, s6, 31
	s_lshl_b64 s[38:39], s[6:7], 6
	s_mov_b64 s[6:7], -1
	s_waitcnt vmcnt(0)
	v_ffbh_u32_e32 v0, v175
	v_min_u32_e32 v0, 32, v0
	v_lshlrev_b64 v[174:175], v0, v[174:175]
	v_min_u32_e32 v174, 1, v174
	v_or_b32_e32 v174, v175, v174
	v_cvt_f32_u32_e32 v174, v174
	v_sub_u32_e32 v0, 32, v0
	v_ldexp_f32 v0, v174, v0
	v_fmamk_f32 v0, v0, 0x2e800000, v176
	v_cmp_gt_f32_e32 vcc, s29, v0
	v_mul_f32_e32 v174, 0x4b800000, v0
	s_nop 0
	v_cndmask_b32_e32 v0, v0, v174, vcc
	v_rsq_f32_e32 v0, v0
	s_nop 0
	v_mul_f32_e32 v174, 0x45800000, v0
	v_cndmask_b32_e32 v0, v0, v174, vcc
	v_pk_mul_f32 v[146:147], v[146:147], v[0:1] op_sel_hi:[1,0]
	v_pk_mul_f32 v[144:145], v[144:145], v[0:1] op_sel_hi:[1,0]
	v_pk_mul_f32 v[142:143], v[142:143], v[0:1] op_sel_hi:[1,0]
	v_pk_mul_f32 v[140:141], v[140:141], v[0:1] op_sel_hi:[1,0]
	v_pk_mul_f32 v[138:139], v[138:139], v[0:1] op_sel_hi:[1,0]
	v_pk_mul_f32 v[136:137], v[136:137], v[0:1] op_sel_hi:[1,0]
	v_pk_mul_f32 v[134:135], v[134:135], v[0:1] op_sel_hi:[1,0]
	v_pk_mul_f32 v[132:133], v[132:133], v[0:1] op_sel_hi:[1,0]
	s_and_b64 vcc, exec, s[10:11]
	s_cbranch_vccz .LBB0_727
	s_and_b64 vcc, exec, s[8:9]
	s_cbranch_vccz .LBB0_724
	s_andn2_b64 vcc, exec, s[66:67]
	s_cbranch_vccnz .LBB0_721
	s_movk_i32 s6, 0xc0
	v_mad_i64_i32 v[174:175], s[6:7], v2, s6, 0
	s_and_b64 vcc, exec, s[20:21]
	s_cbranch_vccz .LBB0_718
	v_mul_f32_e32 v0, 0xbfb8aa3b, v144
	v_exp_f32_e32 v178, v0
	v_mul_f32_e32 v0, 0xbfb8aa3b, v145
	v_exp_f32_e32 v179, v0
	v_mul_f32_e32 v0, 0xbfb8aa3b, v146
	v_exp_f32_e32 v180, v0
	v_mul_f32_e32 v0, 0xbfb8aa3b, v147
	v_pk_add_f32 v[178:179], v[178:179], 1.0 op_sel_hi:[1,0]
	v_exp_f32_e32 v181, v0
	v_div_scale_f32 v0, s[6:7], v179, v179, 1.0
	v_rcp_f32_e32 v177, v0
	v_pk_add_f32 v[180:181], v[180:181], 1.0 op_sel_hi:[1,0]
	v_lshl_add_u64 v[182:183], v[158:159], 0, v[174:175]
	v_fma_f32 v184, -v0, v177, 1.0
	v_fmac_f32_e32 v177, v184, v177
	v_div_scale_f32 v184, vcc, 1.0, v179, 1.0
	v_mul_f32_e32 v185, v184, v177
	v_fma_f32 v186, -v0, v185, v184
	v_fmac_f32_e32 v185, v186, v177
	v_fma_f32 v0, -v0, v185, v184
	v_div_fmas_f32 v0, v0, v177, v185
	v_div_fixup_f32 v179, v0, v179, 1.0
	v_div_scale_f32 v0, s[6:7], v178, v178, 1.0
	v_rcp_f32_e32 v177, v0
	s_nop 0
	v_fma_f32 v184, -v0, v177, 1.0
	v_fmac_f32_e32 v177, v184, v177
	v_div_scale_f32 v184, vcc, 1.0, v178, 1.0
	v_mul_f32_e32 v185, v184, v177
	v_fma_f32 v186, -v0, v185, v184
	v_fmac_f32_e32 v185, v186, v177
	v_fma_f32 v0, -v0, v185, v184
	v_div_fmas_f32 v0, v0, v177, v185
	v_div_fixup_f32 v178, v0, v178, 1.0
	v_div_scale_f32 v0, s[6:7], v181, v181, 1.0
	v_rcp_f32_e32 v177, v0
	s_nop 0
	v_fma_f32 v184, -v0, v177, 1.0
	v_fmac_f32_e32 v177, v184, v177
	v_div_scale_f32 v184, vcc, 1.0, v181, 1.0
	v_mul_f32_e32 v185, v184, v177
	v_fma_f32 v186, -v0, v185, v184
	v_fmac_f32_e32 v185, v186, v177
	v_fma_f32 v0, -v0, v185, v184
	v_div_fmas_f32 v0, v0, v177, v185
	v_div_fixup_f32 v181, v0, v181, 1.0
	v_div_scale_f32 v0, s[6:7], v180, v180, 1.0
	v_rcp_f32_e32 v177, v0
	s_nop 0
	v_fma_f32 v184, -v0, v177, 1.0
	v_fmac_f32_e32 v177, v184, v177
	v_div_scale_f32 v184, vcc, 1.0, v180, 1.0
	v_mul_f32_e32 v185, v184, v177
	v_fma_f32 v186, -v0, v185, v184
	v_fmac_f32_e32 v185, v186, v177
	v_fma_f32 v0, -v0, v185, v184
	v_div_fmas_f32 v0, v0, v177, v185
	v_div_fixup_f32 v180, v0, v180, 1.0
	global_store_dwordx4 v[182:183], v[178:181], off

; __device__ __forceinline__ uint2 pack4(f32x4 v) { return make_uint2(pack2(v[0], v[1]), pack2(v[2], v[3])); }
; __device__ __forceinline__ float rstd_of(const unsigned long long* rowss, int row) {
;   return rsqrtf((float)rowss[row] * (1.f / (SS_FIX * DM)) + 1e-6f);
; }
;   __device__ __forceinline__ void operator()(const AccT& acc_in, const Unit& u, int wr, int wc, int fr, int fq) const {
;     ...
;     for (int ai = 0; ai < 2; ++ai)
; #pragma unroll
;       for (int m = 0; m < 4; ++m) {
;         const int tok = EPI_ROW(u, ai, m);
;         const float rs = rstd_of(rowss, tok);
;         f32x4 acc[2][2][2];
; #pragma unroll
;         for (int bj = 0; bj < 2; ++bj)
; #pragma unroll
;           for (int n = 0; n < 2; ++n) acc[0][bj][n] = acc_in[ai][bj][m][n] * rs;
;         if (u.pn < 4) {
; #pragma unroll
;           for (int bj = 0; bj < 2; ++bj) {
;             const int head = 4 * u.pn + 2 * bj + (wc >> 1);
;             rope_store(acc[0][bj][0], acc[0][bj][1], tok, d1, qn + (size_t)tok * DM + head * 64);
;           }
;         } else if (u.pn == 4) {
; #pragma unroll
;           for (int bj = 0; bj < 2; ++bj)
; #pragma unroll
;             for (int n = 0; n < 2; ++n) *(uint2*)(cbuf + (size_t)tok * 256 + (EPI_COL(u, bj, n) - 1024)) = pack4(acc[0][bj][n]);
;         } else if (u.pn < 7) {
;           u16* kdst = (u.pn == 5) ? ksb : kwb;
;           u16* vdst = (u.pn == 5) ? vsT : vwT;
;           const int gk = wc >> 1;
;           rope_store(acc[0][0][0], acc[0][0][1], tok, d1, kdst + (size_t)tok * 128 + gk * 64);
;           const int b = tok >> 12, t = tok & 4095;
; #pragma unroll
;           for (int n = 0; n < 2; ++n) {
;             const int d = 32 * (wc & 1) + 16 * n + 4 * fq;
; #pragma unroll
;             for (int r = 0; r < 4; ++r) vdst[((size_t)(b * 2 + gk) * 64 + d + r) * SEQ + t] = f2bf(acc[0][1][n][r]);
;           }
;         } else {
; #pragma unroll
;           for (int n = 0; n < 2; ++n) {
;             const int c = 32 * wc + 16 * n + 4 * fq;
;             if (c < 48) {
;               const f32x4 a = acc[0][0][n];
;               float4 gv;
;               gv.x = 1.f / (1.f + __expf(-a[0])); gv.y = 1.f / (1.f + __expf(-a[1]));
;               gv.z = 1.f / (1.f + __expf(-a[2])); gv.w = 1.f / (1.f + __expf(-a[3]));
;               *(float4*)(gbuf + (size_t)tok * 48 + c) = gv;
;             }
;           }
;         }
.LBB0_729:
	v_or_b32_e32 v132, 16, v2
	v_ashrrev_i32_e32 v133, 31, v132
	v_lshl_add_u64 v[134:135], v[132:133], 3, s[12:13]
	v_mov_b64_e32 v[134:135], v[234:235]
	v_cndmask_b32_e64 v136, 0, 1, s[8:9]
	s_mov_b64 s[40:41], -1
	s_andn2_b64 vcc, exec, s[10:11]
	s_waitcnt vmcnt(0)
	v_ffbh_u32_e32 v3, v135
	v_min_u32_e32 v3, 32, v3
	v_lshlrev_b64 v[134:135], v3, v[134:135]
	v_min_u32_e32 v134, 1, v134
	v_or_b32_e32 v134, v135, v134
	v_cvt_f32_u32_e32 v134, v134
	v_sub_u32_e32 v3, 32, v3
	v_cndmask_b32_e64 v135, 0, 1, s[10:11]
	v_cmp_ne_u32_e64 s[8:9], 1, v135
	v_ldexp_f32 v3, v134, v3
	v_fmamk_f32 v3, v3, 0x2e800000, v176
	v_mul_f32_e32 v134, 0x4b800000, v3
	v_cmp_gt_f32_e64 s[6:7], s29, v3
	s_nop 1
	v_cndmask_b32_e64 v3, v3, v134, s[6:7]
	v_rsq_f32_e32 v3, v3
	s_nop 0
	v_mul_f32_e32 v134, 0x45800000, v3
	v_cndmask_b32_e64 v134, v3, v134, s[6:7]
	v_pk_mul_f32 v[130:131], v[130:131], v[134:135] op_sel_hi:[1,0]
	v_pk_mul_f32 v[128:129], v[128:129], v[134:135] op_sel_hi:[1,0]
	v_pk_mul_f32 v[126:127], v[126:127], v[134:135] op_sel_hi:[1,0]
	v_pk_mul_f32 v[124:125], v[124:125], v[134:135] op_sel_hi:[1,0]
	v_pk_mul_f32 v[122:123], v[122:123], v[134:135] op_sel_hi:[1,0]
	v_pk_mul_f32 v[120:121], v[120:121], v[134:135] op_sel_hi:[1,0]
	v_pk_mul_f32 v[118:119], v[118:119], v[134:135] op_sel_hi:[1,0]
	v_pk_mul_f32 v[116:117], v[116:117], v[134:135] op_sel_hi:[1,0]
	v_cmp_ne_u32_e64 s[6:7], 1, v136
	s_cbranch_vccnz .LBB0_743
	s_and_b64 vcc, exec, s[6:7]
	s_mov_b64 s[10:11], -1
	s_cbranch_vccnz .LBB0_740
	s_andn2_b64 vcc, exec, s[66:67]
	s_cbranch_vccnz .LBB0_737
	s_movk_i32 s10, 0xc0
	s_andn2_b64 vcc, exec, s[20:21]
	v_mad_i64_i32 v[134:135], s[10:11], v132, s10, 0
	s_cbranch_vccnz .LBB0_734
	v_mul_f32_e32 v3, 0xbfb8aa3b, v128
	v_exp_f32_e32 v136, v3
	v_mul_f32_e32 v3, 0xbfb8aa3b, v129
	v_exp_f32_e32 v137, v3
	v_mul_f32_e32 v3, 0xbfb8aa3b, v130
	v_exp_f32_e32 v138, v3
	v_mul_f32_e32 v3, 0xbfb8aa3b, v131
	v_pk_add_f32 v[136:137], v[136:137], 1.0 op_sel_hi:[1,0]
	v_exp_f32_e32 v139, v3
	v_div_scale_f32 v3, s[10:11], v137, v137, 1.0
	v_rcp_f32_e32 v142, v3
	v_pk_add_f32 v[138:139], v[138:139], 1.0 op_sel_hi:[1,0]
	v_lshl_add_u64 v[140:141], v[158:159], 0, v[134:135]
	v_fma_f32 v143, -v3, v142, 1.0
	v_fmac_f32_e32 v142, v143, v142
	v_div_scale_f32 v143, vcc, 1.0, v137, 1.0
	v_mul_f32_e32 v144, v143, v142
	v_fma_f32 v145, -v3, v144, v143
	v_fmac_f32_e32 v144, v145, v142
	v_fma_f32 v3, -v3, v144, v143
	v_div_fmas_f32 v3, v3, v142, v144
	v_div_fixup_f32 v137, v3, v137, 1.0
	v_div_scale_f32 v3, s[10:11], v136, v136, 1.0
	v_rcp_f32_e32 v142, v3
	s_nop 0
	v_fma_f32 v143, -v3, v142, 1.0
	v_fmac_f32_e32 v142, v143, v142
	v_div_scale_f32 v143, vcc, 1.0, v136, 1.0
	v_mul_f32_e32 v144, v143, v142
	v_fma_f32 v145, -v3, v144, v143
	v_fmac_f32_e32 v144, v145, v142
	v_fma_f32 v3, -v3, v144, v143
	v_div_fmas_f32 v3, v3, v142, v144
	v_div_fixup_f32 v136, v3, v136, 1.0
	v_div_scale_f32 v3, s[10:11], v139, v139, 1.0
	v_rcp_f32_e32 v142, v3
	s_nop 0
	v_fma_f32 v143, -v3, v142, 1.0
	v_fmac_f32_e32 v142, v143, v142
	v_div_scale_f32 v143, vcc, 1.0, v139, 1.0
	v_mul_f32_e32 v144, v143, v142
	v_fma_f32 v145, -v3, v144, v143
	v_fmac_f32_e32 v144, v145, v142
	v_fma_f32 v3, -v3, v144, v143
	v_div_fmas_f32 v3, v3, v142, v144
	v_div_fixup_f32 v139, v3, v139, 1.0
	v_div_scale_f32 v3, s[10:11], v138, v138, 1.0
	v_rcp_f32_e32 v142, v3
	s_nop 0
	v_fma_f32 v143, -v3, v142, 1.0
	v_fmac_f32_e32 v142, v143, v142
	v_div_scale_f32 v143, vcc, 1.0, v138, 1.0
	v_mul_f32_e32 v144, v143, v142
	v_fma_f32 v145, -v3, v144, v143
	v_fmac_f32_e32 v144, v145, v142
	v_fma_f32 v3, -v3, v144, v143
	v_div_fmas_f32 v3, v3, v142, v144
	v_div_fixup_f32 v138, v3, v138, 1.0
	global_store_dwordx4 v[140:141], v[136:139], off

; __device__ __forceinline__ uint2 pack4(f32x4 v) { return make_uint2(pack2(v[0], v[1]), pack2(v[2], v[3])); }
; __device__ __forceinline__ float rstd_of(const unsigned long long* rowss, int row) {
;   return rsqrtf((float)rowss[row] * (1.f / (SS_FIX * DM)) + 1e-6f);
; }
;   __device__ __forceinline__ void operator()(const AccT& acc_in, const Unit& u, int wr, int wc, int fr, int fq) const {
;     ...
;     for (int ai = 0; ai < 2; ++ai)
; #pragma unroll
;       for (int m = 0; m < 4; ++m) {
;         const int tok = EPI_ROW(u, ai, m);
;         const float rs = rstd_of(rowss, tok);
;         f32x4 acc[2][2][2];
; #pragma unroll
;         for (int bj = 0; bj < 2; ++bj)
; #pragma unroll
;           for (int n = 0; n < 2; ++n) acc[0][bj][n] = acc_in[ai][bj][m][n] * rs;
;         if (u.pn < 4) {
; #pragma unroll
;           for (int bj = 0; bj < 2; ++bj) {
;             const int head = 4 * u.pn + 2 * bj + (wc >> 1);
;             rope_store(acc[0][bj][0], acc[0][bj][1], tok, d1, qn + (size_t)tok * DM + head * 64);
;           }
;         } else if (u.pn == 4) {
; #pragma unroll
;           for (int bj = 0; bj < 2; ++bj)
; #pragma unroll
;             for (int n = 0; n < 2; ++n) *(uint2*)(cbuf + (size_t)tok * 256 + (EPI_COL(u, bj, n) - 1024)) = pack4(acc[0][bj][n]);
;         } else if (u.pn < 7) {
;           u16* kdst = (u.pn == 5) ? ksb : kwb;
;           u16* vdst = (u.pn == 5) ? vsT : vwT;
;           const int gk = wc >> 1;
;           rope_store(acc[0][0][0], acc[0][0][1], tok, d1, kdst + (size_t)tok * 128 + gk * 64);
;           const int b = tok >> 12, t = tok & 4095;
; #pragma unroll
;           for (int n = 0; n < 2; ++n) {
;             const int d = 32 * (wc & 1) + 16 * n + 4 * fq;
; #pragma unroll
;             for (int r = 0; r < 4; ++r) vdst[((size_t)(b * 2 + gk) * 64 + d + r) * SEQ + t] = f2bf(acc[0][1][n][r]);
;           }
;         } else {
; #pragma unroll
;           for (int n = 0; n < 2; ++n) {
;             const int c = 32 * wc + 16 * n + 4 * fq;
;             if (c < 48) {
;               const f32x4 a = acc[0][0][n];
;               float4 gv;
;               gv.x = 1.f / (1.f + __expf(-a[0])); gv.y = 1.f / (1.f + __expf(-a[1]));
;               gv.z = 1.f / (1.f + __expf(-a[2])); gv.w = 1.f / (1.f + __expf(-a[3]));
;               *(float4*)(gbuf + (size_t)tok * 48 + c) = gv;
;             }
;           }
;         }
.LBB0_745:
	v_or_b32_e32 v116, 32, v2
	v_ashrrev_i32_e32 v117, 31, v116
	v_lshl_add_u64 v[118:119], v[116:117], 3, s[12:13]
	v_mov_b64_e32 v[118:119], v[236:237]
	s_and_b64 vcc, exec, s[8:9]
	s_waitcnt vmcnt(0)
	v_ffbh_u32_e32 v3, v119
	v_min_u32_e32 v3, 32, v3
	v_lshlrev_b64 v[118:119], v3, v[118:119]
	v_min_u32_e32 v118, 1, v118
	v_or_b32_e32 v118, v119, v118
	v_cvt_f32_u32_e32 v118, v118
	v_sub_u32_e32 v3, 32, v3
	v_ldexp_f32 v3, v118, v3
	v_fmamk_f32 v3, v3, 0x2e800000, v176
	v_mul_f32_e32 v118, 0x4b800000, v3
	v_cmp_gt_f32_e64 s[10:11], s29, v3
	s_nop 1
	v_cndmask_b32_e64 v3, v3, v118, s[10:11]
	v_rsq_f32_e32 v3, v3
	s_nop 0
	v_mul_f32_e32 v118, 0x45800000, v3
	v_cndmask_b32_e64 v118, v3, v118, s[10:11]
	v_pk_mul_f32 v[114:115], v[114:115], v[118:119] op_sel_hi:[1,0]
	v_pk_mul_f32 v[112:113], v[112:113], v[118:119] op_sel_hi:[1,0]
	v_pk_mul_f32 v[110:111], v[110:111], v[118:119] op_sel_hi:[1,0]
	v_pk_mul_f32 v[108:109], v[108:109], v[118:119] op_sel_hi:[1,0]
	v_pk_mul_f32 v[106:107], v[106:107], v[118:119] op_sel_hi:[1,0]
	v_pk_mul_f32 v[104:105], v[104:105], v[118:119] op_sel_hi:[1,0]
	v_pk_mul_f32 v[102:103], v[102:103], v[118:119] op_sel_hi:[1,0]
	v_pk_mul_f32 v[100:101], v[100:101], v[118:119] op_sel_hi:[1,0]
	s_mov_b64 s[10:11], -1
	s_cbranch_vccnz .LBB0_759
	s_and_b64 vcc, exec, s[6:7]
	s_cbranch_vccnz .LBB0_756
	s_andn2_b64 vcc, exec, s[66:67]
	s_cbranch_vccnz .LBB0_753
	s_movk_i32 s10, 0xc0
	s_andn2_b64 vcc, exec, s[20:21]
	v_mad_i64_i32 v[118:119], s[10:11], v116, s10, 0
	s_cbranch_vccnz .LBB0_750
	v_mul_f32_e32 v3, 0xbfb8aa3b, v112
	v_exp_f32_e32 v120, v3
	v_mul_f32_e32 v3, 0xbfb8aa3b, v113
	v_exp_f32_e32 v121, v3
	v_mul_f32_e32 v3, 0xbfb8aa3b, v114
	v_exp_f32_e32 v122, v3
	v_mul_f32_e32 v3, 0xbfb8aa3b, v115
	v_pk_add_f32 v[120:121], v[120:121], 1.0 op_sel_hi:[1,0]
	v_exp_f32_e32 v123, v3
	v_div_scale_f32 v3, s[10:11], v121, v121, 1.0
	v_rcp_f32_e32 v126, v3
	v_pk_add_f32 v[122:123], v[122:123], 1.0 op_sel_hi:[1,0]
	v_lshl_add_u64 v[124:125], v[158:159], 0, v[118:119]
	v_fma_f32 v127, -v3, v126, 1.0
	v_fmac_f32_e32 v126, v127, v126
	v_div_scale_f32 v127, vcc, 1.0, v121, 1.0
	v_mul_f32_e32 v128, v127, v126
	v_fma_f32 v129, -v3, v128, v127
	v_fmac_f32_e32 v128, v129, v126
	v_fma_f32 v3, -v3, v128, v127
	v_div_fmas_f32 v3, v3, v126, v128
	v_div_fixup_f32 v121, v3, v121, 1.0
	v_div_scale_f32 v3, s[10:11], v120, v120, 1.0
	v_rcp_f32_e32 v126, v3
	s_nop 0
	v_fma_f32 v127, -v3, v126, 1.0
	v_fmac_f32_e32 v126, v127, v126
	v_div_scale_f32 v127, vcc, 1.0, v120, 1.0
	v_mul_f32_e32 v128, v127, v126
	v_fma_f32 v129, -v3, v128, v127
	v_fmac_f32_e32 v128, v129, v126
	v_fma_f32 v3, -v3, v128, v127
	v_div_fmas_f32 v3, v3, v126, v128
	v_div_fixup_f32 v120, v3, v120, 1.0
	v_div_scale_f32 v3, s[10:11], v123, v123, 1.0
	v_rcp_f32_e32 v126, v3
	s_nop 0
	v_fma_f32 v127, -v3, v126, 1.0
	v_fmac_f32_e32 v126, v127, v126
	v_div_scale_f32 v127, vcc, 1.0, v123, 1.0
	v_mul_f32_e32 v128, v127, v126
	v_fma_f32 v129, -v3, v128, v127
	v_fmac_f32_e32 v128, v129, v126
	v_fma_f32 v3, -v3, v128, v127
	v_div_fmas_f32 v3, v3, v126, v128
	v_div_fixup_f32 v123, v3, v123, 1.0
	v_div_scale_f32 v3, s[10:11], v122, v122, 1.0
	v_rcp_f32_e32 v126, v3
	s_nop 0
	v_fma_f32 v127, -v3, v126, 1.0
	v_fmac_f32_e32 v126, v127, v126
	v_div_scale_f32 v127, vcc, 1.0, v122, 1.0
	v_mul_f32_e32 v128, v127, v126
	v_fma_f32 v129, -v3, v128, v127
	v_fmac_f32_e32 v128, v129, v126
	v_fma_f32 v3, -v3, v128, v127
	v_div_fmas_f32 v3, v3, v126, v128
	v_div_fixup_f32 v122, v3, v122, 1.0
	global_store_dwordx4 v[124:125], v[120:123], off

; __device__ __forceinline__ uint2 pack4(f32x4 v) { return make_uint2(pack2(v[0], v[1]), pack2(v[2], v[3])); }
; __device__ __forceinline__ float rstd_of(const unsigned long long* rowss, int row) {
;   return rsqrtf((float)rowss[row] * (1.f / (SS_FIX * DM)) + 1e-6f);
; }
;   __device__ __forceinline__ void operator()(const AccT& acc_in, const Unit& u, int wr, int wc, int fr, int fq) const {
;     ...
;     for (int ai = 0; ai < 2; ++ai)
; #pragma unroll
;       for (int m = 0; m < 4; ++m) {
;         const int tok = EPI_ROW(u, ai, m);
;         const float rs = rstd_of(rowss, tok);
;         f32x4 acc[2][2][2];
; #pragma unroll
;         for (int bj = 0; bj < 2; ++bj)
; #pragma unroll
;           for (int n = 0; n < 2; ++n) acc[0][bj][n] = acc_in[ai][bj][m][n] * rs;
;         if (u.pn < 4) {
; #pragma unroll
;           for (int bj = 0; bj < 2; ++bj) {
;             const int head = 4 * u.pn + 2 * bj + (wc >> 1);
;             rope_store(acc[0][bj][0], acc[0][bj][1], tok, d1, qn + (size_t)tok * DM + head * 64);
;           }
;         } else if (u.pn == 4) {
; #pragma unroll
;           for (int bj = 0; bj < 2; ++bj)
; #pragma unroll
;             for (int n = 0; n < 2; ++n) *(uint2*)(cbuf + (size_t)tok * 256 + (EPI_COL(u, bj, n) - 1024)) = pack4(acc[0][bj][n]);
;         } else if (u.pn < 7) {
;           u16* kdst = (u.pn == 5) ? ksb : kwb;
;           u16* vdst = (u.pn == 5) ? vsT : vwT;
;           const int gk = wc >> 1;
;           rope_store(acc[0][0][0], acc[0][0][1], tok, d1, kdst + (size_t)tok * 128 + gk * 64);
;           const int b = tok >> 12, t = tok & 4095;
; #pragma unroll
;           for (int n = 0; n < 2; ++n) {
;             const int d = 32 * (wc & 1) + 16 * n + 4 * fq;
; #pragma unroll
;             for (int r = 0; r < 4; ++r) vdst[((size_t)(b * 2 + gk) * 64 + d + r) * SEQ + t] = f2bf(acc[0][1][n][r]);
;           }
;         } else {
; #pragma unroll
;           for (int n = 0; n < 2; ++n) {
;             const int c = 32 * wc + 16 * n + 4 * fq;
;             if (c < 48) {
;               const f32x4 a = acc[0][0][n];
;               float4 gv;
;               gv.x = 1.f / (1.f + __expf(-a[0])); gv.y = 1.f / (1.f + __expf(-a[1]));
;               gv.z = 1.f / (1.f + __expf(-a[2])); gv.w = 1.f / (1.f + __expf(-a[3]));
;               *(float4*)(gbuf + (size_t)tok * 48 + c) = gv;
;             }
;           }
;         }
.LBB0_761:
	v_or_b32_e32 v100, 48, v2
	v_ashrrev_i32_e32 v101, 31, v100
	v_lshl_add_u64 v[2:3], v[100:101], 3, s[12:13]
	v_mov_b64_e32 v[2:3], v[238:239]
	s_and_b64 vcc, exec, s[8:9]
	s_waitcnt vmcnt(0)
	v_ffbh_u32_e32 v102, v3
	v_min_u32_e32 v102, 32, v102
	v_lshlrev_b64 v[2:3], v102, v[2:3]
	v_min_u32_e32 v2, 1, v2
	v_or_b32_e32 v2, v3, v2
	v_cvt_f32_u32_e32 v2, v2
	v_sub_u32_e32 v3, 32, v102
	v_ldexp_f32 v2, v2, v3
	v_fmamk_f32 v2, v2, 0x2e800000, v176
	v_mul_f32_e32 v3, 0x4b800000, v2
	v_cmp_gt_f32_e64 s[10:11], s29, v2
	s_nop 1
	v_cndmask_b32_e64 v2, v2, v3, s[10:11]
	v_rsq_f32_e32 v2, v2
	s_nop 0
	v_mul_f32_e32 v3, 0x45800000, v2
	v_cndmask_b32_e64 v102, v2, v3, s[10:11]
	v_pk_mul_f32 v[98:99], v[98:99], v[102:103] op_sel_hi:[1,0]
	v_pk_mul_f32 v[96:97], v[96:97], v[102:103] op_sel_hi:[1,0]
	v_pk_mul_f32 v[94:95], v[94:95], v[102:103] op_sel_hi:[1,0]
	v_pk_mul_f32 v[92:93], v[92:93], v[102:103] op_sel_hi:[1,0]
	v_pk_mul_f32 v[2:3], v[90:91], v[102:103] op_sel_hi:[1,0]
	v_pk_mul_f32 v[88:89], v[88:89], v[102:103] op_sel_hi:[1,0]
	v_pk_mul_f32 v[86:87], v[86:87], v[102:103] op_sel_hi:[1,0]
	v_pk_mul_f32 v[84:85], v[84:85], v[102:103] op_sel_hi:[1,0]
	s_mov_b64 s[10:11], -1
	s_cbranch_vccnz .LBB0_775
	s_and_b64 vcc, exec, s[6:7]
	s_cbranch_vccnz .LBB0_772
	s_andn2_b64 vcc, exec, s[66:67]
	s_cbranch_vccnz .LBB0_769
	s_movk_i32 s10, 0xc0
	s_andn2_b64 vcc, exec, s[20:21]
	v_mad_i64_i32 v[90:91], s[10:11], v100, s10, 0
	s_cbranch_vccnz .LBB0_766
	v_mul_f32_e32 v102, 0xbfb8aa3b, v96
	v_mul_f32_e32 v103, 0xbfb8aa3b, v97
	v_exp_f32_e32 v102, v102
	v_exp_f32_e32 v103, v103
	v_mul_f32_e32 v104, 0xbfb8aa3b, v98
	v_mul_f32_e32 v105, 0xbfb8aa3b, v99
	v_exp_f32_e32 v104, v104
	v_pk_add_f32 v[102:103], v[102:103], 1.0 op_sel_hi:[1,0]
	v_exp_f32_e32 v105, v105
	v_div_scale_f32 v108, s[10:11], v103, v103, 1.0
	v_rcp_f32_e32 v109, v108
	v_pk_add_f32 v[104:105], v[104:105], 1.0 op_sel_hi:[1,0]
	v_lshl_add_u64 v[106:107], v[158:159], 0, v[90:91]
	v_fma_f32 v110, -v108, v109, 1.0
	v_fmac_f32_e32 v109, v110, v109
	v_div_scale_f32 v110, vcc, 1.0, v103, 1.0
	v_mul_f32_e32 v111, v110, v109
	v_fma_f32 v112, -v108, v111, v110
	v_fmac_f32_e32 v111, v112, v109
	v_fma_f32 v108, -v108, v111, v110
	v_div_fmas_f32 v108, v108, v109, v111
	v_div_fixup_f32 v103, v108, v103, 1.0
	v_div_scale_f32 v108, s[10:11], v102, v102, 1.0
	v_rcp_f32_e32 v109, v108
	s_nop 0
	v_fma_f32 v110, -v108, v109, 1.0
	v_fmac_f32_e32 v109, v110, v109
	v_div_scale_f32 v110, vcc, 1.0, v102, 1.0
	v_mul_f32_e32 v111, v110, v109
	v_fma_f32 v112, -v108, v111, v110
	v_fmac_f32_e32 v111, v112, v109
	v_fma_f32 v108, -v108, v111, v110
	v_div_fmas_f32 v108, v108, v109, v111
	v_div_fixup_f32 v102, v108, v102, 1.0
	v_div_scale_f32 v108, s[10:11], v105, v105, 1.0
	v_rcp_f32_e32 v109, v108
	s_nop 0
	v_fma_f32 v110, -v108, v109, 1.0
	v_fmac_f32_e32 v109, v110, v109
	v_div_scale_f32 v110, vcc, 1.0, v105, 1.0
	v_mul_f32_e32 v111, v110, v109
	v_fma_f32 v112, -v108, v111, v110
	v_fmac_f32_e32 v111, v112, v109
	v_fma_f32 v108, -v108, v111, v110
	v_div_fmas_f32 v108, v108, v109, v111
	v_div_fixup_f32 v105, v108, v105, 1.0
	v_div_scale_f32 v108, s[10:11], v104, v104, 1.0
	v_rcp_f32_e32 v109, v108
	s_nop 0
	v_fma_f32 v110, -v108, v109, 1.0
	v_fmac_f32_e32 v109, v110, v109
	v_div_scale_f32 v110, vcc, 1.0, v104, 1.0
	v_mul_f32_e32 v111, v110, v109
	v_fma_f32 v112, -v108, v111, v110
	v_fmac_f32_e32 v111, v112, v109
	v_fma_f32 v108, -v108, v111, v110
	v_div_fmas_f32 v108, v108, v109, v111
	v_div_fixup_f32 v104, v108, v104, 1.0
	global_store_dwordx4 v[106:107], v[102:105], off

; __device__ __forceinline__ uint2 pack4(f32x4 v) { return make_uint2(pack2(v[0], v[1]), pack2(v[2], v[3])); }
; __device__ __forceinline__ float rstd_of(const unsigned long long* rowss, int row) {
;   return rsqrtf((float)rowss[row] * (1.f / (SS_FIX * DM)) + 1e-6f);
; }
;   __device__ __forceinline__ void operator()(const AccT& acc_in, const Unit& u, int wr, int wc, int fr, int fq) const {
;     ...
;     for (int ai = 0; ai < 2; ++ai)
; #pragma unroll
;       for (int m = 0; m < 4; ++m) {
;         const int tok = EPI_ROW(u, ai, m);
;         const float rs = rstd_of(rowss, tok);
;         f32x4 acc[2][2][2];
; #pragma unroll
;         for (int bj = 0; bj < 2; ++bj)
; #pragma unroll
;           for (int n = 0; n < 2; ++n) acc[0][bj][n] = acc_in[ai][bj][m][n] * rs;
;         if (u.pn < 4) {
; #pragma unroll
;           for (int bj = 0; bj < 2; ++bj) {
;             const int head = 4 * u.pn + 2 * bj + (wc >> 1);
;             rope_store(acc[0][bj][0], acc[0][bj][1], tok, d1, qn + (size_t)tok * DM + head * 64);
;           }
;         } else if (u.pn == 4) {
; #pragma unroll
;           for (int bj = 0; bj < 2; ++bj)
; #pragma unroll
;             for (int n = 0; n < 2; ++n) *(uint2*)(cbuf + (size_t)tok * 256 + (EPI_COL(u, bj, n) - 1024)) = pack4(acc[0][bj][n]);
;         } else if (u.pn < 7) {
;           u16* kdst = (u.pn == 5) ? ksb : kwb;
;           u16* vdst = (u.pn == 5) ? vsT : vwT;
;           const int gk = wc >> 1;
;           rope_store(acc[0][0][0], acc[0][0][1], tok, d1, kdst + (size_t)tok * 128 + gk * 64);
;           const int b = tok >> 12, t = tok & 4095;
; #pragma unroll
;           for (int n = 0; n < 2; ++n) {
;             const int d = 32 * (wc & 1) + 16 * n + 4 * fq;
; #pragma unroll
;             for (int r = 0; r < 4; ++r) vdst[((size_t)(b * 2 + gk) * 64 + d + r) * SEQ + t] = f2bf(acc[0][1][n][r]);
;           }
;         } else {
; #pragma unroll
;           for (int n = 0; n < 2; ++n) {
;             const int c = 32 * wc + 16 * n + 4 * fq;
;             if (c < 48) {
;               const f32x4 a = acc[0][0][n];
;               float4 gv;
;               gv.x = 1.f / (1.f + __expf(-a[0])); gv.y = 1.f / (1.f + __expf(-a[1]));
;               gv.z = 1.f / (1.f + __expf(-a[2])); gv.w = 1.f / (1.f + __expf(-a[3]));
;               *(float4*)(gbuf + (size_t)tok * 48 + c) = gv;
;             }
;           }
;         }
.LBB0_777:
	s_addk_i32 s27, 0x80
	v_or_b32_e32 v2, s27, v153
	v_ashrrev_i32_e32 v3, 31, v2
	v_lshl_add_u64 v[84:85], v[2:3], 3, s[12:13]
	v_mov_b64_e32 v[84:85], v[240:241]
	s_ashr_i32 s10, s27, 11
	s_and_b32 s10, s10, -2
	s_or_b32 s10, s10, s79
	s_ashr_i32 s11, s10, 31
	s_lshl_b64 s[38:39], s[10:11], 6
	s_mov_b64 s[10:11], -1
	s_waitcnt vmcnt(0)
	v_ffbh_u32_e32 v86, v85
	v_min_u32_e32 v86, 32, v86
	v_lshlrev_b64 v[84:85], v86, v[84:85]
	v_min_u32_e32 v84, 1, v84
	v_or_b32_e32 v84, v85, v84
	v_cvt_f32_u32_e32 v84, v84
	v_sub_u32_e32 v85, 32, v86
	v_ldexp_f32 v84, v84, v85
	v_fmamk_f32 v84, v84, 0x2e800000, v176
	v_cmp_gt_f32_e32 vcc, s29, v84
	v_mul_f32_e32 v85, 0x4b800000, v84
	s_nop 0
	v_cndmask_b32_e32 v84, v84, v85, vcc
	v_rsq_f32_e32 v84, v84
	s_nop 0
	v_mul_f32_e32 v85, 0x45800000, v84
	v_cndmask_b32_e32 v84, v84, v85, vcc
	v_pk_mul_f32 v[82:83], v[82:83], v[84:85] op_sel_hi:[1,0]
	v_pk_mul_f32 v[80:81], v[80:81], v[84:85] op_sel_hi:[1,0]
	v_pk_mul_f32 v[78:79], v[78:79], v[84:85] op_sel_hi:[1,0]
	v_pk_mul_f32 v[76:77], v[76:77], v[84:85] op_sel_hi:[1,0]
	v_pk_mul_f32 v[74:75], v[74:75], v[84:85] op_sel_hi:[1,0]
	v_pk_mul_f32 v[72:73], v[72:73], v[84:85] op_sel_hi:[1,0]
	v_pk_mul_f32 v[70:71], v[70:71], v[84:85] op_sel_hi:[1,0]
	v_pk_mul_f32 v[68:69], v[68:69], v[84:85] op_sel_hi:[1,0]
	s_and_b64 vcc, exec, s[8:9]
	s_cbranch_vccnz .LBB0_791
	s_and_b64 vcc, exec, s[6:7]
	s_cbranch_vccnz .LBB0_788
	s_andn2_b64 vcc, exec, s[66:67]
	s_cbranch_vccnz .LBB0_785
	s_movk_i32 s10, 0xc0
	s_andn2_b64 vcc, exec, s[20:21]
	v_mad_i64_i32 v[84:85], s[10:11], v2, s10, 0
	s_cbranch_vccnz .LBB0_782
	v_mul_f32_e32 v86, 0xbfb8aa3b, v80
	v_mul_f32_e32 v87, 0xbfb8aa3b, v81
	v_exp_f32_e32 v86, v86
	v_exp_f32_e32 v87, v87
	v_mul_f32_e32 v88, 0xbfb8aa3b, v82
	v_mul_f32_e32 v89, 0xbfb8aa3b, v83
	v_exp_f32_e32 v88, v88
	v_pk_add_f32 v[86:87], v[86:87], 1.0 op_sel_hi:[1,0]
	v_exp_f32_e32 v89, v89
	v_div_scale_f32 v92, s[10:11], v87, v87, 1.0
	v_rcp_f32_e32 v93, v92
	v_pk_add_f32 v[88:89], v[88:89], 1.0 op_sel_hi:[1,0]
	v_lshl_add_u64 v[90:91], v[158:159], 0, v[84:85]
	v_fma_f32 v94, -v92, v93, 1.0
	v_fmac_f32_e32 v93, v94, v93
	v_div_scale_f32 v94, vcc, 1.0, v87, 1.0
	v_mul_f32_e32 v95, v94, v93
	v_fma_f32 v96, -v92, v95, v94
	v_fmac_f32_e32 v95, v96, v93
	v_fma_f32 v92, -v92, v95, v94
	v_div_fmas_f32 v92, v92, v93, v95
	v_div_fixup_f32 v87, v92, v87, 1.0
	v_div_scale_f32 v92, s[10:11], v86, v86, 1.0
	v_rcp_f32_e32 v93, v92
	s_nop 0
	v_fma_f32 v94, -v92, v93, 1.0
	v_fmac_f32_e32 v93, v94, v93
	v_div_scale_f32 v94, vcc, 1.0, v86, 1.0
	v_mul_f32_e32 v95, v94, v93
	v_fma_f32 v96, -v92, v95, v94
	v_fmac_f32_e32 v95, v96, v93
	v_fma_f32 v92, -v92, v95, v94
	v_div_fmas_f32 v92, v92, v93, v95
	v_div_fixup_f32 v86, v92, v86, 1.0
	v_div_scale_f32 v92, s[10:11], v89, v89, 1.0
	v_rcp_f32_e32 v93, v92
	s_nop 0
	v_fma_f32 v94, -v92, v93, 1.0
	v_fmac_f32_e32 v93, v94, v93
	v_div_scale_f32 v94, vcc, 1.0, v89, 1.0
	v_mul_f32_e32 v95, v94, v93
	v_fma_f32 v96, -v92, v95, v94
	v_fmac_f32_e32 v95, v96, v93
	v_fma_f32 v92, -v92, v95, v94
	v_div_fmas_f32 v92, v92, v93, v95
	v_div_fixup_f32 v89, v92, v89, 1.0
	v_div_scale_f32 v92, s[10:11], v88, v88, 1.0
	v_rcp_f32_e32 v93, v92
	s_nop 0
	v_fma_f32 v94, -v92, v93, 1.0
	v_fmac_f32_e32 v93, v94, v93
	v_div_scale_f32 v94, vcc, 1.0, v88, 1.0
	v_mul_f32_e32 v95, v94, v93
	v_fma_f32 v96, -v92, v95, v94
	v_fmac_f32_e32 v95, v96, v93
	v_fma_f32 v92, -v92, v95, v94
	v_div_fmas_f32 v92, v92, v93, v95
	v_div_fixup_f32 v88, v92, v88, 1.0
	global_store_dwordx4 v[90:91], v[86:89], off

; __device__ __forceinline__ uint2 pack4(f32x4 v) { return make_uint2(pack2(v[0], v[1]), pack2(v[2], v[3])); }
; __device__ __forceinline__ float rstd_of(const unsigned long long* rowss, int row) {
;   return rsqrtf((float)rowss[row] * (1.f / (SS_FIX * DM)) + 1e-6f);
; }
;   __device__ __forceinline__ void operator()(const AccT& acc_in, const Unit& u, int wr, int wc, int fr, int fq) const {
;     ...
;     for (int ai = 0; ai < 2; ++ai)
; #pragma unroll
;       for (int m = 0; m < 4; ++m) {
;         const int tok = EPI_ROW(u, ai, m);
;         const float rs = rstd_of(rowss, tok);
;         f32x4 acc[2][2][2];
; #pragma unroll
;         for (int bj = 0; bj < 2; ++bj)
; #pragma unroll
;           for (int n = 0; n < 2; ++n) acc[0][bj][n] = acc_in[ai][bj][m][n] * rs;
;         if (u.pn < 4) {
; #pragma unroll
;           for (int bj = 0; bj < 2; ++bj) {
;             const int head = 4 * u.pn + 2 * bj + (wc >> 1);
;             rope_store(acc[0][bj][0], acc[0][bj][1], tok, d1, qn + (size_t)tok * DM + head * 64);
;           }
;         } else if (u.pn == 4) {
; #pragma unroll
;           for (int bj = 0; bj < 2; ++bj)
; #pragma unroll
;             for (int n = 0; n < 2; ++n) *(uint2*)(cbuf + (size_t)tok * 256 + (EPI_COL(u, bj, n) - 1024)) = pack4(acc[0][bj][n]);
;         } else if (u.pn < 7) {
;           u16* kdst = (u.pn == 5) ? ksb : kwb;
;           u16* vdst = (u.pn == 5) ? vsT : vwT;
;           const int gk = wc >> 1;
;           rope_store(acc[0][0][0], acc[0][0][1], tok, d1, kdst + (size_t)tok * 128 + gk * 64);
;           const int b = tok >> 12, t = tok & 4095;
; #pragma unroll
;           for (int n = 0; n < 2; ++n) {
;             const int d = 32 * (wc & 1) + 16 * n + 4 * fq;
; #pragma unroll
;             for (int r = 0; r < 4; ++r) vdst[((size_t)(b * 2 + gk) * 64 + d + r) * SEQ + t] = f2bf(acc[0][1][n][r]);
;           }
;         } else {
; #pragma unroll
;           for (int n = 0; n < 2; ++n) {
;             const int c = 32 * wc + 16 * n + 4 * fq;
;             if (c < 48) {
;               const f32x4 a = acc[0][0][n];
;               float4 gv;
;               gv.x = 1.f / (1.f + __expf(-a[0])); gv.y = 1.f / (1.f + __expf(-a[1]));
;               gv.z = 1.f / (1.f + __expf(-a[2])); gv.w = 1.f / (1.f + __expf(-a[3]));
;               *(float4*)(gbuf + (size_t)tok * 48 + c) = gv;
;             }
;           }
;         }
.LBB0_793:
	v_or_b32_e32 v68, 16, v2
	v_ashrrev_i32_e32 v69, 31, v68
	v_lshl_add_u64 v[70:71], v[68:69], 3, s[12:13]
	v_mov_b64_e32 v[70:71], v[242:243]
	s_and_b64 vcc, exec, s[8:9]
	s_waitcnt vmcnt(0)
	v_ffbh_u32_e32 v3, v71
	v_min_u32_e32 v3, 32, v3
	v_lshlrev_b64 v[70:71], v3, v[70:71]
	v_min_u32_e32 v70, 1, v70
	v_or_b32_e32 v70, v71, v70
	v_cvt_f32_u32_e32 v70, v70
	v_sub_u32_e32 v3, 32, v3
	v_ldexp_f32 v3, v70, v3
	v_fmamk_f32 v3, v3, 0x2e800000, v176
	v_mul_f32_e32 v70, 0x4b800000, v3
	v_cmp_gt_f32_e64 s[10:11], s29, v3
	s_nop 1
	v_cndmask_b32_e64 v3, v3, v70, s[10:11]
	v_rsq_f32_e32 v3, v3
	s_nop 0
	v_mul_f32_e32 v70, 0x45800000, v3
	v_cndmask_b32_e64 v70, v3, v70, s[10:11]
	v_pk_mul_f32 v[66:67], v[66:67], v[70:71] op_sel_hi:[1,0]
	v_pk_mul_f32 v[64:65], v[64:65], v[70:71] op_sel_hi:[1,0]
	v_pk_mul_f32 v[62:63], v[62:63], v[70:71] op_sel_hi:[1,0]
	v_pk_mul_f32 v[60:61], v[60:61], v[70:71] op_sel_hi:[1,0]
	v_pk_mul_f32 v[58:59], v[58:59], v[70:71] op_sel_hi:[1,0]
	v_pk_mul_f32 v[56:57], v[56:57], v[70:71] op_sel_hi:[1,0]
	v_pk_mul_f32 v[54:55], v[54:55], v[70:71] op_sel_hi:[1,0]
	v_pk_mul_f32 v[52:53], v[52:53], v[70:71] op_sel_hi:[1,0]
	s_mov_b64 s[10:11], -1
	s_cbranch_vccnz .LBB0_807
	s_and_b64 vcc, exec, s[6:7]
	s_cbranch_vccnz .LBB0_804
	s_andn2_b64 vcc, exec, s[66:67]
	s_cbranch_vccnz .LBB0_801
	s_movk_i32 s10, 0xc0
	s_andn2_b64 vcc, exec, s[20:21]
	v_mad_i64_i32 v[70:71], s[10:11], v68, s10, 0
	s_cbranch_vccnz .LBB0_798
	v_mul_f32_e32 v3, 0xbfb8aa3b, v64
	v_exp_f32_e32 v72, v3
	v_mul_f32_e32 v3, 0xbfb8aa3b, v65
	v_exp_f32_e32 v73, v3
	v_mul_f32_e32 v3, 0xbfb8aa3b, v66
	v_exp_f32_e32 v74, v3
	v_mul_f32_e32 v3, 0xbfb8aa3b, v67
	v_pk_add_f32 v[72:73], v[72:73], 1.0 op_sel_hi:[1,0]
	v_exp_f32_e32 v75, v3
	v_div_scale_f32 v3, s[10:11], v73, v73, 1.0
	v_rcp_f32_e32 v78, v3
	v_pk_add_f32 v[74:75], v[74:75], 1.0 op_sel_hi:[1,0]
	v_lshl_add_u64 v[76:77], v[158:159], 0, v[70:71]
	v_fma_f32 v79, -v3, v78, 1.0
	v_fmac_f32_e32 v78, v79, v78
	v_div_scale_f32 v79, vcc, 1.0, v73, 1.0
	v_mul_f32_e32 v80, v79, v78
	v_fma_f32 v81, -v3, v80, v79
	v_fmac_f32_e32 v80, v81, v78
	v_fma_f32 v3, -v3, v80, v79
	v_div_fmas_f32 v3, v3, v78, v80
	v_div_fixup_f32 v73, v3, v73, 1.0
	v_div_scale_f32 v3, s[10:11], v72, v72, 1.0
	v_rcp_f32_e32 v78, v3
	s_nop 0
	v_fma_f32 v79, -v3, v78, 1.0
	v_fmac_f32_e32 v78, v79, v78
	v_div_scale_f32 v79, vcc, 1.0, v72, 1.0
	v_mul_f32_e32 v80, v79, v78
	v_fma_f32 v81, -v3, v80, v79
	v_fmac_f32_e32 v80, v81, v78
	v_fma_f32 v3, -v3, v80, v79
	v_div_fmas_f32 v3, v3, v78, v80
	v_div_fixup_f32 v72, v3, v72, 1.0
	v_div_scale_f32 v3, s[10:11], v75, v75, 1.0
	v_rcp_f32_e32 v78, v3
	s_nop 0
	v_fma_f32 v79, -v3, v78, 1.0
	v_fmac_f32_e32 v78, v79, v78
	v_div_scale_f32 v79, vcc, 1.0, v75, 1.0
	v_mul_f32_e32 v80, v79, v78
	v_fma_f32 v81, -v3, v80, v79
	v_fmac_f32_e32 v80, v81, v78
	v_fma_f32 v3, -v3, v80, v79
	v_div_fmas_f32 v3, v3, v78, v80
	v_div_fixup_f32 v75, v3, v75, 1.0
	v_div_scale_f32 v3, s[10:11], v74, v74, 1.0
	v_rcp_f32_e32 v78, v3
	s_nop 0
	v_fma_f32 v79, -v3, v78, 1.0
	v_fmac_f32_e32 v78, v79, v78
	v_div_scale_f32 v79, vcc, 1.0, v74, 1.0
	v_mul_f32_e32 v80, v79, v78
	v_fma_f32 v81, -v3, v80, v79
	v_fmac_f32_e32 v80, v81, v78
	v_fma_f32 v3, -v3, v80, v79
	v_div_fmas_f32 v3, v3, v78, v80
	v_div_fixup_f32 v74, v3, v74, 1.0
	global_store_dwordx4 v[76:77], v[72:75], off

; __device__ __forceinline__ uint2 pack4(f32x4 v) { return make_uint2(pack2(v[0], v[1]), pack2(v[2], v[3])); }
; __device__ __forceinline__ float rstd_of(const unsigned long long* rowss, int row) {
;   return rsqrtf((float)rowss[row] * (1.f / (SS_FIX * DM)) + 1e-6f);
; }
;   __device__ __forceinline__ void operator()(const AccT& acc_in, const Unit& u, int wr, int wc, int fr, int fq) const {
;     ...
;     for (int ai = 0; ai < 2; ++ai)
; #pragma unroll
;       for (int m = 0; m < 4; ++m) {
;         const int tok = EPI_ROW(u, ai, m);
;         const float rs = rstd_of(rowss, tok);
;         f32x4 acc[2][2][2];
; #pragma unroll
;         for (int bj = 0; bj < 2; ++bj)
; #pragma unroll
;           for (int n = 0; n < 2; ++n) acc[0][bj][n] = acc_in[ai][bj][m][n] * rs;
;         if (u.pn < 4) {
; #pragma unroll
;           for (int bj = 0; bj < 2; ++bj) {
;             const int head = 4 * u.pn + 2 * bj + (wc >> 1);
;             rope_store(acc[0][bj][0], acc[0][bj][1], tok, d1, qn + (size_t)tok * DM + head * 64);
;           }
;         } else if (u.pn == 4) {
; #pragma unroll
;           for (int bj = 0; bj < 2; ++bj)
; #pragma unroll
;             for (int n = 0; n < 2; ++n) *(uint2*)(cbuf + (size_t)tok * 256 + (EPI_COL(u, bj, n) - 1024)) = pack4(acc[0][bj][n]);
;         } else if (u.pn < 7) {
;           u16* kdst = (u.pn == 5) ? ksb : kwb;
;           u16* vdst = (u.pn == 5) ? vsT : vwT;
;           const int gk = wc >> 1;
;           rope_store(acc[0][0][0], acc[0][0][1], tok, d1, kdst + (size_t)tok * 128 + gk * 64);
;           const int b = tok >> 12, t = tok & 4095;
; #pragma unroll
;           for (int n = 0; n < 2; ++n) {
;             const int d = 32 * (wc & 1) + 16 * n + 4 * fq;
; #pragma unroll
;             for (int r = 0; r < 4; ++r) vdst[((size_t)(b * 2 + gk) * 64 + d + r) * SEQ + t] = f2bf(acc[0][1][n][r]);
;           }
;         } else {
; #pragma unroll
;           for (int n = 0; n < 2; ++n) {
;             const int c = 32 * wc + 16 * n + 4 * fq;
;             if (c < 48) {
;               const f32x4 a = acc[0][0][n];
;               float4 gv;
;               gv.x = 1.f / (1.f + __expf(-a[0])); gv.y = 1.f / (1.f + __expf(-a[1]));
;               gv.z = 1.f / (1.f + __expf(-a[2])); gv.w = 1.f / (1.f + __expf(-a[3]));
;               *(float4*)(gbuf + (size_t)tok * 48 + c) = gv;
;             }
;           }
;         }
.LBB0_809:
	v_or_b32_e32 v52, 32, v2
	v_ashrrev_i32_e32 v53, 31, v52
	v_lshl_add_u64 v[54:55], v[52:53], 3, s[12:13]
	v_mov_b64_e32 v[54:55], v[244:245]
	s_and_b64 vcc, exec, s[8:9]
	s_waitcnt vmcnt(0)
	v_ffbh_u32_e32 v3, v55
	v_min_u32_e32 v3, 32, v3
	v_lshlrev_b64 v[54:55], v3, v[54:55]
	v_min_u32_e32 v54, 1, v54
	v_or_b32_e32 v54, v55, v54
	v_cvt_f32_u32_e32 v54, v54
	v_sub_u32_e32 v3, 32, v3
	v_ldexp_f32 v3, v54, v3
	v_fmamk_f32 v3, v3, 0x2e800000, v176
	v_mul_f32_e32 v54, 0x4b800000, v3
	v_cmp_gt_f32_e64 s[10:11], s29, v3
	s_nop 1
	v_cndmask_b32_e64 v3, v3, v54, s[10:11]
	v_rsq_f32_e32 v3, v3
	s_nop 0
	v_mul_f32_e32 v54, 0x45800000, v3
	v_cndmask_b32_e64 v54, v3, v54, s[10:11]
	v_pk_mul_f32 v[50:51], v[50:51], v[54:55] op_sel_hi:[1,0]
	v_pk_mul_f32 v[48:49], v[48:49], v[54:55] op_sel_hi:[1,0]
	v_pk_mul_f32 v[46:47], v[46:47], v[54:55] op_sel_hi:[1,0]
	v_pk_mul_f32 v[44:45], v[44:45], v[54:55] op_sel_hi:[1,0]
	v_pk_mul_f32 v[42:43], v[42:43], v[54:55] op_sel_hi:[1,0]
	v_pk_mul_f32 v[40:41], v[40:41], v[54:55] op_sel_hi:[1,0]
	v_pk_mul_f32 v[38:39], v[38:39], v[54:55] op_sel_hi:[1,0]
	v_pk_mul_f32 v[36:37], v[36:37], v[54:55] op_sel_hi:[1,0]
	s_mov_b64 s[10:11], -1
	s_cbranch_vccnz .LBB0_823
	s_and_b64 vcc, exec, s[6:7]
	s_cbranch_vccnz .LBB0_820
	s_andn2_b64 vcc, exec, s[66:67]
	s_cbranch_vccnz .LBB0_817
	s_movk_i32 s10, 0xc0
	s_andn2_b64 vcc, exec, s[20:21]
	v_mad_i64_i32 v[54:55], s[10:11], v52, s10, 0
	s_cbranch_vccnz .LBB0_814
	v_mul_f32_e32 v3, 0xbfb8aa3b, v48
	v_exp_f32_e32 v56, v3
	v_mul_f32_e32 v3, 0xbfb8aa3b, v49
	v_exp_f32_e32 v57, v3
	v_mul_f32_e32 v3, 0xbfb8aa3b, v50
	v_exp_f32_e32 v58, v3
	v_mul_f32_e32 v3, 0xbfb8aa3b, v51
	v_pk_add_f32 v[56:57], v[56:57], 1.0 op_sel_hi:[1,0]
	v_exp_f32_e32 v59, v3
	v_div_scale_f32 v3, s[10:11], v57, v57, 1.0
	v_rcp_f32_e32 v62, v3
	v_pk_add_f32 v[58:59], v[58:59], 1.0 op_sel_hi:[1,0]
	v_lshl_add_u64 v[60:61], v[158:159], 0, v[54:55]
	v_fma_f32 v63, -v3, v62, 1.0
	v_fmac_f32_e32 v62, v63, v62
	v_div_scale_f32 v63, vcc, 1.0, v57, 1.0
	v_mul_f32_e32 v64, v63, v62
	v_fma_f32 v65, -v3, v64, v63
	v_fmac_f32_e32 v64, v65, v62
	v_fma_f32 v3, -v3, v64, v63
	v_div_fmas_f32 v3, v3, v62, v64
	v_div_fixup_f32 v57, v3, v57, 1.0
	v_div_scale_f32 v3, s[10:11], v56, v56, 1.0
	v_rcp_f32_e32 v62, v3
	s_nop 0
	v_fma_f32 v63, -v3, v62, 1.0
	v_fmac_f32_e32 v62, v63, v62
	v_div_scale_f32 v63, vcc, 1.0, v56, 1.0
	v_mul_f32_e32 v64, v63, v62
	v_fma_f32 v65, -v3, v64, v63
	v_fmac_f32_e32 v64, v65, v62
	v_fma_f32 v3, -v3, v64, v63
	v_div_fmas_f32 v3, v3, v62, v64
	v_div_fixup_f32 v56, v3, v56, 1.0
	v_div_scale_f32 v3, s[10:11], v59, v59, 1.0
	v_rcp_f32_e32 v62, v3
	s_nop 0
	v_fma_f32 v63, -v3, v62, 1.0
	v_fmac_f32_e32 v62, v63, v62
	v_div_scale_f32 v63, vcc, 1.0, v59, 1.0
	v_mul_f32_e32 v64, v63, v62
	v_fma_f32 v65, -v3, v64, v63
	v_fmac_f32_e32 v64, v65, v62
	v_fma_f32 v3, -v3, v64, v63
	v_div_fmas_f32 v3, v3, v62, v64
	v_div_fixup_f32 v59, v3, v59, 1.0
	v_div_scale_f32 v3, s[10:11], v58, v58, 1.0
	v_rcp_f32_e32 v62, v3
	s_nop 0
	v_fma_f32 v63, -v3, v62, 1.0
	v_fmac_f32_e32 v62, v63, v62
	v_div_scale_f32 v63, vcc, 1.0, v58, 1.0
	v_mul_f32_e32 v64, v63, v62
	v_fma_f32 v65, -v3, v64, v63
	v_fmac_f32_e32 v64, v65, v62
	v_fma_f32 v3, -v3, v64, v63
	v_div_fmas_f32 v3, v3, v62, v64
	v_div_fixup_f32 v58, v3, v58, 1.0
	global_store_dwordx4 v[60:61], v[56:59], off

; __device__ __forceinline__ uint2 pack4(f32x4 v) { return make_uint2(pack2(v[0], v[1]), pack2(v[2], v[3])); }
; __device__ __forceinline__ float rstd_of(const unsigned long long* rowss, int row) {
;   return rsqrtf((float)rowss[row] * (1.f / (SS_FIX * DM)) + 1e-6f);
; }
;   __device__ __forceinline__ void operator()(const AccT& acc_in, const Unit& u, int wr, int wc, int fr, int fq) const {
;     ...
;     for (int ai = 0; ai < 2; ++ai)
; #pragma unroll
;       for (int m = 0; m < 4; ++m) {
;         const int tok = EPI_ROW(u, ai, m);
;         const float rs = rstd_of(rowss, tok);
;         f32x4 acc[2][2][2];
; #pragma unroll
;         for (int bj = 0; bj < 2; ++bj)
; #pragma unroll
;           for (int n = 0; n < 2; ++n) acc[0][bj][n] = acc_in[ai][bj][m][n] * rs;
;         if (u.pn < 4) {
; #pragma unroll
;           for (int bj = 0; bj < 2; ++bj) {
;             const int head = 4 * u.pn + 2 * bj + (wc >> 1);
;             rope_store(acc[0][bj][0], acc[0][bj][1], tok, d1, qn + (size_t)tok * DM + head * 64);
;           }
;         } else if (u.pn == 4) {
; #pragma unroll
;           for (int bj = 0; bj < 2; ++bj)
; #pragma unroll
;             for (int n = 0; n < 2; ++n) *(uint2*)(cbuf + (size_t)tok * 256 + (EPI_COL(u, bj, n) - 1024)) = pack4(acc[0][bj][n]);
;         } else if (u.pn < 7) {
;           u16* kdst = (u.pn == 5) ? ksb : kwb;
;           u16* vdst = (u.pn == 5) ? vsT : vwT;
;           const int gk = wc >> 1;
;           rope_store(acc[0][0][0], acc[0][0][1], tok, d1, kdst + (size_t)tok * 128 + gk * 64);
;           const int b = tok >> 12, t = tok & 4095;
; #pragma unroll
;           for (int n = 0; n < 2; ++n) {
;             const int d = 32 * (wc & 1) + 16 * n + 4 * fq;
; #pragma unroll
;             for (int r = 0; r < 4; ++r) vdst[((size_t)(b * 2 + gk) * 64 + d + r) * SEQ + t] = f2bf(acc[0][1][n][r]);
;           }
;         } else {
; #pragma unroll
;           for (int n = 0; n < 2; ++n) {
;             const int c = 32 * wc + 16 * n + 4 * fq;
;             if (c < 48) {
;               const f32x4 a = acc[0][0][n];
;               float4 gv;
;               gv.x = 1.f / (1.f + __expf(-a[0])); gv.y = 1.f / (1.f + __expf(-a[1]));
;               gv.z = 1.f / (1.f + __expf(-a[2])); gv.w = 1.f / (1.f + __expf(-a[3]));
;               *(float4*)(gbuf + (size_t)tok * 48 + c) = gv;
;             }
;           }
;         }
.LBB0_825:
	v_or_b32_e32 v36, 48, v2
	v_ashrrev_i32_e32 v37, 31, v36
	v_lshl_add_u64 v[2:3], v[36:37], 3, s[12:13]
	v_mov_b64_e32 v[2:3], v[246:247]
	s_and_b64 vcc, exec, s[8:9]
	s_mov_b64 s[8:9], -1
	s_waitcnt vmcnt(0)
	v_ffbh_u32_e32 v38, v3
	v_min_u32_e32 v38, 32, v38
	v_lshlrev_b64 v[2:3], v38, v[2:3]
	v_min_u32_e32 v2, 1, v2
	v_or_b32_e32 v2, v3, v2
	v_cvt_f32_u32_e32 v2, v2
	v_sub_u32_e32 v3, 32, v38
	v_ldexp_f32 v2, v2, v3
	v_fmamk_f32 v2, v2, 0x2e800000, v176
	v_mul_f32_e32 v3, 0x4b800000, v2
	v_cmp_gt_f32_e64 s[10:11], s29, v2
	s_nop 1
	v_cndmask_b32_e64 v2, v2, v3, s[10:11]
	v_rsq_f32_e32 v2, v2
	s_nop 0
	v_mul_f32_e32 v3, 0x45800000, v2
	v_cndmask_b32_e64 v38, v2, v3, s[10:11]
	v_pk_mul_f32 v[34:35], v[34:35], v[38:39] op_sel_hi:[1,0]
	v_pk_mul_f32 v[32:33], v[32:33], v[38:39] op_sel_hi:[1,0]
	v_pk_mul_f32 v[30:31], v[30:31], v[38:39] op_sel_hi:[1,0]
	v_pk_mul_f32 v[28:29], v[28:29], v[38:39] op_sel_hi:[1,0]
	v_pk_mul_f32 v[2:3], v[26:27], v[38:39] op_sel_hi:[1,0]
	v_pk_mul_f32 v[24:25], v[24:25], v[38:39] op_sel_hi:[1,0]
	v_pk_mul_f32 v[22:23], v[22:23], v[38:39] op_sel_hi:[1,0]
	v_pk_mul_f32 v[20:21], v[20:21], v[38:39] op_sel_hi:[1,0]
	s_cbranch_vccnz .LBB0_839
	s_and_b64 vcc, exec, s[6:7]
	s_mov_b64 s[6:7], -1
	s_cbranch_vccnz .LBB0_836
	s_andn2_b64 vcc, exec, s[66:67]
	s_cbranch_vccnz .LBB0_833
	s_movk_i32 s6, 0xc0
	s_andn2_b64 vcc, exec, s[20:21]
	v_mad_i64_i32 v[26:27], s[6:7], v36, s6, 0
	s_cbranch_vccnz .LBB0_830
	v_mul_f32_e32 v38, 0xbfb8aa3b, v32
	v_mul_f32_e32 v39, 0xbfb8aa3b, v33
	v_exp_f32_e32 v38, v38
	v_exp_f32_e32 v39, v39
	v_mul_f32_e32 v40, 0xbfb8aa3b, v34
	v_mul_f32_e32 v41, 0xbfb8aa3b, v35
	v_exp_f32_e32 v40, v40
	v_pk_add_f32 v[38:39], v[38:39], 1.0 op_sel_hi:[1,0]
	v_exp_f32_e32 v41, v41
	v_div_scale_f32 v44, s[6:7], v39, v39, 1.0
	v_rcp_f32_e32 v45, v44
	v_pk_add_f32 v[40:41], v[40:41], 1.0 op_sel_hi:[1,0]
	v_lshl_add_u64 v[42:43], v[158:159], 0, v[26:27]
	v_fma_f32 v46, -v44, v45, 1.0
	v_fmac_f32_e32 v45, v46, v45
	v_div_scale_f32 v46, vcc, 1.0, v39, 1.0
	v_mul_f32_e32 v47, v46, v45
	v_fma_f32 v48, -v44, v47, v46
	v_fmac_f32_e32 v47, v48, v45
	v_fma_f32 v44, -v44, v47, v46
	v_div_fmas_f32 v44, v44, v45, v47
	v_div_fixup_f32 v39, v44, v39, 1.0
	v_div_scale_f32 v44, s[6:7], v38, v38, 1.0
	v_rcp_f32_e32 v45, v44
	s_nop 0
	v_fma_f32 v46, -v44, v45, 1.0
	v_fmac_f32_e32 v45, v46, v45
	v_div_scale_f32 v46, vcc, 1.0, v38, 1.0
	v_mul_f32_e32 v47, v46, v45
	v_fma_f32 v48, -v44, v47, v46
	v_fmac_f32_e32 v47, v48, v45
	v_fma_f32 v44, -v44, v47, v46
	v_div_fmas_f32 v44, v44, v45, v47
	v_div_fixup_f32 v38, v44, v38, 1.0
	v_div_scale_f32 v44, s[6:7], v41, v41, 1.0
	v_rcp_f32_e32 v45, v44
	s_nop 0
	v_fma_f32 v46, -v44, v45, 1.0
	v_fmac_f32_e32 v45, v46, v45
	v_div_scale_f32 v46, vcc, 1.0, v41, 1.0
	v_mul_f32_e32 v47, v46, v45
	v_fma_f32 v48, -v44, v47, v46
	v_fmac_f32_e32 v47, v48, v45
	v_fma_f32 v44, -v44, v47, v46
	v_div_fmas_f32 v44, v44, v45, v47
	v_div_fixup_f32 v41, v44, v41, 1.0
	v_div_scale_f32 v44, s[6:7], v40, v40, 1.0
	v_rcp_f32_e32 v45, v44
	s_nop 0
	v_fma_f32 v46, -v44, v45, 1.0
	v_fmac_f32_e32 v45, v46, v45
	v_div_scale_f32 v46, vcc, 1.0, v40, 1.0
	v_mul_f32_e32 v47, v46, v45
	v_fma_f32 v48, -v44, v47, v46
	v_fmac_f32_e32 v47, v48, v45
	v_fma_f32 v44, -v44, v47, v46
	v_div_fmas_f32 v44, v44, v45, v47
	v_div_fixup_f32 v40, v44, v40, 1.0
	global_store_dwordx4 v[42:43], v[38:41], off
